# v22 plus GLU epilogue and layer-0 out-proj epilogue: residual / gate loads requested up front with counted waits
# baseline (speedup 1.0000x reference)
; __device__ __forceinline__ unsigned cvt_pk_bf16(float lo, float hi) { unsigned r; asm volatile("v_cvt_pk_bf16_f32 %0, %1, %2" : "=v"(r) : "v"(lo), "v"(hi)); return r; }
; __device__ __forceinline__ float sigm(float v) { return __builtin_amdgcn_rcpf(1.0f + __builtin_amdgcn_exp2f(-1.4426950408889634f * v)); }
;     __device__ __forceinline__ void operator()(const f32x4 (&acc)[2][2][4][2], const Unit& u, int wr, int wc, int fr, int fq) const {
;         typedef unsigned u32x2 __attribute__((ext_vector_type(2)));
;         const int row0 = u.pm * BM + wr * 64 + fr, col0 = wc * 32 + 8 * fq;
; #pragma unroll
;         for (int bj = 0; bj < 2; ++bj)
; #pragma unroll
;             for (int n = 0; n < 2; ++n) {
;                 const int c = col0 + bj * HALF + 4 * n;
;                 const f32x4 bv = *(const f32x4*)(bias + c);
; #pragma unroll
;                 for (int ai = 0; ai < 2; ++ai)
; #pragma unroll
;                     for (int m = 0; m < 4; ++m) {
;                         const size_t row = (size_t)(row0 + ai * HALF + m * 16);
;                         const f32x4 v = acc[ai][bj][m][n] + bv;
;                         const u32x2 yv = *(const u32x2*)(YGS + row * 256 + c);
;                         const float y0 = __uint_as_float(yv.x << 16), y1 = __uint_as_float(yv.x & 0xffff0000u), y2 = __uint_as_float(yv.y << 16), y3 = __uint_as_float(yv.y & 0xffff0000u);
;                         u32x2 w; w.x = cvt_pk_bf16(y0 * sigm(v[0]), y1 * sigm(v[1])); w.y = cvt_pk_bf16(y2 * sigm(v[2]), y3 * sigm(v[3]));
;                         *(u32x2*)(MIX + row * 1024 + 256 + c) = w;
.LBB0_843:
	v_lshl_add_u32 v154, s54, 8, v156
	s_and_b64 vcc, exec, s[0:1]
	s_mov_b64 s[0:1], -1
	global_load_dwordx4 v[128:131], v[138:139], off
	global_load_dwordx4 v[208:211], v[138:139], off offset:16
	v_lshlrev_b32_e32 v220, 9, v154
	v_lshl_add_u64 v[148:149], v[140:141], 0, v[220:221]
	global_load_dwordx2 v[160:161], v[148:149], off
	v_or_b32_e32 v152, 16, v154
	v_lshlrev_b32_e32 v220, 9, v152
	v_lshl_add_u64 v[148:149], v[140:141], 0, v[220:221]
	global_load_dwordx2 v[162:163], v[148:149], off
	v_or_b32_e32 v152, 32, v154
	v_lshlrev_b32_e32 v220, 9, v152
	v_lshl_add_u64 v[148:149], v[140:141], 0, v[220:221]
	global_load_dwordx2 v[164:165], v[148:149], off
	v_or_b32_e32 v152, 48, v154
	v_lshlrev_b32_e32 v220, 9, v152
	v_lshl_add_u64 v[148:149], v[140:141], 0, v[220:221]
	global_load_dwordx2 v[166:167], v[148:149], off
	v_or_b32_e32 v152, 0x80, v154
	v_lshlrev_b32_e32 v220, 9, v152
	v_lshl_add_u64 v[148:149], v[140:141], 0, v[220:221]
	global_load_dwordx2 v[168:169], v[148:149], off
	v_or_b32_e32 v152, 0x90, v154
	v_lshlrev_b32_e32 v220, 9, v152
	v_lshl_add_u64 v[148:149], v[140:141], 0, v[220:221]
	global_load_dwordx2 v[170:171], v[148:149], off
	v_or_b32_e32 v152, 0xa0, v154
	v_lshlrev_b32_e32 v220, 9, v152
	v_lshl_add_u64 v[148:149], v[140:141], 0, v[220:221]
	global_load_dwordx2 v[172:173], v[148:149], off
	v_or_b32_e32 v152, 0xb0, v154
	v_lshlrev_b32_e32 v220, 9, v152
	v_lshl_add_u64 v[148:149], v[140:141], 0, v[220:221]
	global_load_dwordx2 v[174:175], v[148:149], off
	v_lshlrev_b32_e32 v220, 9, v154
	v_lshl_add_u64 v[148:149], v[140:141], 0, v[220:221]
	global_load_dwordx2 v[176:177], v[148:149], off offset:8
	v_or_b32_e32 v152, 16, v154
	v_lshlrev_b32_e32 v220, 9, v152
	v_lshl_add_u64 v[148:149], v[140:141], 0, v[220:221]
	global_load_dwordx2 v[178:179], v[148:149], off offset:8
	v_or_b32_e32 v152, 32, v154
	v_lshlrev_b32_e32 v220, 9, v152
	v_lshl_add_u64 v[148:149], v[140:141], 0, v[220:221]
	global_load_dwordx2 v[180:181], v[148:149], off offset:8
	v_or_b32_e32 v152, 48, v154
	v_lshlrev_b32_e32 v220, 9, v152
	v_lshl_add_u64 v[148:149], v[140:141], 0, v[220:221]
	global_load_dwordx2 v[182:183], v[148:149], off offset:8
	v_or_b32_e32 v152, 0x80, v154
	v_lshlrev_b32_e32 v220, 9, v152
	v_lshl_add_u64 v[148:149], v[140:141], 0, v[220:221]
	global_load_dwordx2 v[184:185], v[148:149], off offset:8
	v_or_b32_e32 v152, 0x90, v154
	v_lshlrev_b32_e32 v220, 9, v152
	v_lshl_add_u64 v[148:149], v[140:141], 0, v[220:221]
	global_load_dwordx2 v[186:187], v[148:149], off offset:8
	v_or_b32_e32 v152, 0xa0, v154
	v_lshlrev_b32_e32 v220, 9, v152
	v_lshl_add_u64 v[148:149], v[140:141], 0, v[220:221]
	global_load_dwordx2 v[188:189], v[148:149], off offset:8
	v_or_b32_e32 v152, 0xb0, v154
	v_lshlrev_b32_e32 v220, 9, v152
	v_lshl_add_u64 v[148:149], v[140:141], 0, v[220:221]
	global_load_dwordx2 v[190:191], v[148:149], off offset:8
	v_lshlrev_b32_e32 v220, 9, v154
	v_lshl_add_u64 v[148:149], v[140:141], 0, v[220:221]
	global_load_dwordx2 v[192:193], v[148:149], off offset:256
	v_or_b32_e32 v152, 16, v154
	v_lshlrev_b32_e32 v220, 9, v152
	v_lshl_add_u64 v[148:149], v[140:141], 0, v[220:221]
	global_load_dwordx2 v[194:195], v[148:149], off offset:256
	v_or_b32_e32 v152, 32, v154
	v_lshlrev_b32_e32 v220, 9, v152
	v_lshl_add_u64 v[148:149], v[140:141], 0, v[220:221]
	global_load_dwordx2 v[196:197], v[148:149], off offset:256
	v_or_b32_e32 v152, 48, v154
	v_lshlrev_b32_e32 v220, 9, v152
	v_lshl_add_u64 v[148:149], v[140:141], 0, v[220:221]
	global_load_dwordx2 v[198:199], v[148:149], off offset:256
	v_or_b32_e32 v152, 0x80, v154
	v_lshlrev_b32_e32 v220, 9, v152
	v_lshl_add_u64 v[148:149], v[140:141], 0, v[220:221]
	global_load_dwordx2 v[200:201], v[148:149], off offset:256
	v_or_b32_e32 v152, 0x90, v154
	v_lshlrev_b32_e32 v220, 9, v152
	v_lshl_add_u64 v[148:149], v[140:141], 0, v[220:221]
	global_load_dwordx2 v[202:203], v[148:149], off offset:256
	v_or_b32_e32 v152, 0xa0, v154
	v_lshlrev_b32_e32 v220, 9, v152
	v_lshl_add_u64 v[148:149], v[140:141], 0, v[220:221]
	global_load_dwordx2 v[204:205], v[148:149], off offset:256
	v_or_b32_e32 v152, 0xb0, v154
	v_lshlrev_b32_e32 v220, 9, v152
	v_lshl_add_u64 v[148:149], v[140:141], 0, v[220:221]
	global_load_dwordx2 v[206:207], v[148:149], off offset:256
	s_waitcnt vmcnt(16)
; __device__ __forceinline__ unsigned cvt_pk_bf16(float lo, float hi) { unsigned r; asm volatile("v_cvt_pk_bf16_f32 %0, %1, %2" : "=v"(r) : "v"(lo), "v"(hi)); return r; }
; __device__ __forceinline__ float sigm(float v) { return __builtin_amdgcn_rcpf(1.0f + __builtin_amdgcn_exp2f(-1.4426950408889634f * v)); }
;     __device__ __forceinline__ void operator()(const f32x4 (&acc)[2][2][4][2], const Unit& u, int wr, int wc, int fr, int fq) const {
;     ...
;                 const f32x4 bv = *(const f32x4*)(bias + c);
; #pragma unroll
;                 for (int ai = 0; ai < 2; ++ai)
; #pragma unroll
;                     for (int m = 0; m < 4; ++m) {
;                         const size_t row = (size_t)(row0 + ai * HALF + m * 16);
;                         const f32x4 v = acc[ai][bj][m][n] + bv;
;                         const u32x2 yv = *(const u32x2*)(YGS + row * 256 + c);
;                         const float y0 = __uint_as_float(yv.x << 16), y1 = __uint_as_float(yv.x & 0xffff0000u), y2 = __uint_as_float(yv.y << 16), y3 = __uint_as_float(yv.y & 0xffff0000u);
;                         u32x2 w; w.x = cvt_pk_bf16(y0 * sigm(v[0]), y1 * sigm(v[1])); w.y = cvt_pk_bf16(y2 * sigm(v[2]), y3 * sigm(v[3]));
;                         *(u32x2*)(MIX + row * 1024 + 256 + c) = w;
;                         if (m & 1) asm volatile("" ::: "memory");
	v_pk_add_f32 v[124:125], v[124:125], v[128:129]
	v_pk_add_f32 v[126:127], v[126:127], v[130:131]
	v_mul_f32_e32 v124, 0xbfb8aa3b, v124
	v_mul_f32_e32 v125, 0xbfb8aa3b, v125
	v_mul_f32_e32 v126, 0xbfb8aa3b, v126
	v_mul_f32_e32 v127, 0xbfb8aa3b, v127
	v_exp_f32_e32 v124, v124
	v_exp_f32_e32 v125, v125
	v_exp_f32_e32 v126, v126
	v_exp_f32_e32 v127, v127
	v_add_f32_e32 v124, 1.0, v124
	v_add_f32_e32 v125, 1.0, v125
	v_add_f32_e32 v126, 1.0, v126
	v_add_f32_e32 v127, 1.0, v127
	v_rcp_f32_e32 v124, v124
	v_rcp_f32_e32 v125, v125
	v_rcp_f32_e32 v126, v126
	v_rcp_f32_e32 v127, v127
	v_lshlrev_b32_e32 v153, 16, v160
	v_and_b32_e32 v160, 0xffff0000, v160
	v_lshlrev_b32_e32 v155, 16, v161
	v_and_b32_e32 v161, 0xffff0000, v161
	v_mul_f32_e32 v124, v124, v153
	v_mul_f32_e32 v125, v125, v160
	v_mul_f32_e32 v126, v126, v155
	v_mul_f32_e32 v127, v127, v161
	v_cvt_pk_bf16_f32 v124, v124, v125
	v_cvt_pk_bf16_f32 v125, v126, v127
	v_lshlrev_b32_e32 v220, 11, v154
	v_lshl_add_u64 v[150:151], v[142:143], 0, v[220:221]
	global_store_dwordx2 v[150:151], v[124:125], off offset:512
	v_pk_add_f32 v[120:121], v[120:121], v[128:129]
	v_pk_add_f32 v[122:123], v[122:123], v[130:131]
	v_mul_f32_e32 v120, 0xbfb8aa3b, v120
	v_mul_f32_e32 v121, 0xbfb8aa3b, v121
	v_mul_f32_e32 v122, 0xbfb8aa3b, v122
	v_mul_f32_e32 v123, 0xbfb8aa3b, v123
	v_exp_f32_e32 v120, v120
	v_exp_f32_e32 v121, v121
	v_exp_f32_e32 v122, v122
	v_exp_f32_e32 v123, v123
	v_add_f32_e32 v120, 1.0, v120
	v_add_f32_e32 v121, 1.0, v121
	v_add_f32_e32 v122, 1.0, v122
	v_add_f32_e32 v123, 1.0, v123
	v_rcp_f32_e32 v120, v120
	v_rcp_f32_e32 v121, v121
	v_rcp_f32_e32 v122, v122
	v_rcp_f32_e32 v123, v123
	v_lshlrev_b32_e32 v153, 16, v162
	v_and_b32_e32 v162, 0xffff0000, v162
	v_lshlrev_b32_e32 v155, 16, v163
	v_and_b32_e32 v163, 0xffff0000, v163
	v_mul_f32_e32 v120, v120, v153
	v_mul_f32_e32 v121, v121, v162
	v_mul_f32_e32 v122, v122, v155
	v_mul_f32_e32 v123, v123, v163
	v_cvt_pk_bf16_f32 v120, v120, v121
	v_cvt_pk_bf16_f32 v121, v122, v123
	v_or_b32_e32 v152, 16, v154
	v_lshlrev_b32_e32 v220, 11, v152
	v_lshl_add_u64 v[150:151], v[142:143], 0, v[220:221]
	global_store_dwordx2 v[150:151], v[120:121], off offset:512
	v_pk_add_f32 v[116:117], v[116:117], v[128:129]
	v_pk_add_f32 v[118:119], v[118:119], v[130:131]
	v_mul_f32_e32 v116, 0xbfb8aa3b, v116
	v_mul_f32_e32 v117, 0xbfb8aa3b, v117
	v_mul_f32_e32 v118, 0xbfb8aa3b, v118
	v_mul_f32_e32 v119, 0xbfb8aa3b, v119
	v_exp_f32_e32 v116, v116
	v_exp_f32_e32 v117, v117
	v_exp_f32_e32 v118, v118
	v_exp_f32_e32 v119, v119
	v_add_f32_e32 v116, 1.0, v116
	v_add_f32_e32 v117, 1.0, v117
	v_add_f32_e32 v118, 1.0, v118
	v_add_f32_e32 v119, 1.0, v119
	v_rcp_f32_e32 v116, v116
	v_rcp_f32_e32 v117, v117
	v_rcp_f32_e32 v118, v118
	v_rcp_f32_e32 v119, v119
	v_lshlrev_b32_e32 v153, 16, v164
	v_and_b32_e32 v164, 0xffff0000, v164
	v_lshlrev_b32_e32 v155, 16, v165
	v_and_b32_e32 v165, 0xffff0000, v165
	v_mul_f32_e32 v116, v116, v153
	v_mul_f32_e32 v117, v117, v164
	v_mul_f32_e32 v118, v118, v155
	v_mul_f32_e32 v119, v119, v165
	v_cvt_pk_bf16_f32 v116, v116, v117
	v_cvt_pk_bf16_f32 v117, v118, v119
	v_or_b32_e32 v152, 32, v154
	v_lshlrev_b32_e32 v220, 11, v152
	v_lshl_add_u64 v[150:151], v[142:143], 0, v[220:221]
	global_store_dwordx2 v[150:151], v[116:117], off offset:512
	v_pk_add_f32 v[112:113], v[112:113], v[128:129]
	v_pk_add_f32 v[114:115], v[114:115], v[130:131]
	v_mul_f32_e32 v112, 0xbfb8aa3b, v112
	v_mul_f32_e32 v113, 0xbfb8aa3b, v113
	v_mul_f32_e32 v114, 0xbfb8aa3b, v114
	v_mul_f32_e32 v115, 0xbfb8aa3b, v115
	v_exp_f32_e32 v112, v112
	v_exp_f32_e32 v113, v113
	v_exp_f32_e32 v114, v114
	v_exp_f32_e32 v115, v115
	v_add_f32_e32 v112, 1.0, v112
	v_add_f32_e32 v113, 1.0, v113
	v_add_f32_e32 v114, 1.0, v114
	v_add_f32_e32 v115, 1.0, v115
	v_rcp_f32_e32 v112, v112
	v_rcp_f32_e32 v113, v113
	v_rcp_f32_e32 v114, v114
	v_rcp_f32_e32 v115, v115
	v_lshlrev_b32_e32 v153, 16, v166
	v_and_b32_e32 v166, 0xffff0000, v166
	v_lshlrev_b32_e32 v155, 16, v167
	v_and_b32_e32 v167, 0xffff0000, v167
	v_mul_f32_e32 v112, v112, v153
	v_mul_f32_e32 v113, v113, v166
	v_mul_f32_e32 v114, v114, v155
	v_mul_f32_e32 v115, v115, v167
	v_cvt_pk_bf16_f32 v112, v112, v113
	v_cvt_pk_bf16_f32 v113, v114, v115
	v_or_b32_e32 v152, 48, v154
	v_lshlrev_b32_e32 v220, 11, v152
	v_lshl_add_u64 v[150:151], v[142:143], 0, v[220:221]
	global_store_dwordx2 v[150:151], v[112:113], off offset:512
	v_pk_add_f32 v[108:109], v[108:109], v[128:129]
	v_pk_add_f32 v[110:111], v[110:111], v[130:131]
	v_mul_f32_e32 v108, 0xbfb8aa3b, v108
	v_mul_f32_e32 v109, 0xbfb8aa3b, v109
	v_mul_f32_e32 v110, 0xbfb8aa3b, v110
	v_mul_f32_e32 v111, 0xbfb8aa3b, v111
	v_exp_f32_e32 v108, v108
	v_exp_f32_e32 v109, v109
	v_exp_f32_e32 v110, v110
	v_exp_f32_e32 v111, v111
	v_add_f32_e32 v108, 1.0, v108
	v_add_f32_e32 v109, 1.0, v109
	v_add_f32_e32 v110, 1.0, v110
	v_add_f32_e32 v111, 1.0, v111
	v_rcp_f32_e32 v108, v108
	v_rcp_f32_e32 v109, v109
	v_rcp_f32_e32 v110, v110
	v_rcp_f32_e32 v111, v111
	v_lshlrev_b32_e32 v153, 16, v168
	v_and_b32_e32 v168, 0xffff0000, v168
	v_lshlrev_b32_e32 v155, 16, v169
	v_and_b32_e32 v169, 0xffff0000, v169
	v_mul_f32_e32 v108, v108, v153
	v_mul_f32_e32 v109, v109, v168
	v_mul_f32_e32 v110, v110, v155
	v_mul_f32_e32 v111, v111, v169
	v_cvt_pk_bf16_f32 v108, v108, v109
	v_cvt_pk_bf16_f32 v109, v110, v111
	v_or_b32_e32 v152, 0x80, v154
	v_lshlrev_b32_e32 v220, 11, v152
	v_lshl_add_u64 v[150:151], v[142:143], 0, v[220:221]
	global_store_dwordx2 v[150:151], v[108:109], off offset:512
	v_pk_add_f32 v[104:105], v[104:105], v[128:129]
	v_pk_add_f32 v[106:107], v[106:107], v[130:131]
	v_mul_f32_e32 v104, 0xbfb8aa3b, v104
; __device__ __forceinline__ unsigned cvt_pk_bf16(float lo, float hi) { unsigned r; asm volatile("v_cvt_pk_bf16_f32 %0, %1, %2" : "=v"(r) : "v"(lo), "v"(hi)); return r; }
; __device__ __forceinline__ float sigm(float v) { return __builtin_amdgcn_rcpf(1.0f + __builtin_amdgcn_exp2f(-1.4426950408889634f * v)); }
;     __device__ __forceinline__ void operator()(const f32x4 (&acc)[2][2][4][2], const Unit& u, int wr, int wc, int fr, int fq) const {
;     ...
;         for (int bj = 0; bj < 2; ++bj)
; #pragma unroll
;             for (int n = 0; n < 2; ++n) {
;                 const int c = col0 + bj * HALF + 4 * n;
;                 const f32x4 bv = *(const f32x4*)(bias + c);
; #pragma unroll
;                 for (int ai = 0; ai < 2; ++ai)
; #pragma unroll
;                     for (int m = 0; m < 4; ++m) {
;                         const size_t row = (size_t)(row0 + ai * HALF + m * 16);
;                         const f32x4 v = acc[ai][bj][m][n] + bv;
;                         const u32x2 yv = *(const u32x2*)(YGS + row * 256 + c);
;                         const float y0 = __uint_as_float(yv.x << 16), y1 = __uint_as_float(yv.x & 0xffff0000u), y2 = __uint_as_float(yv.y << 16), y3 = __uint_as_float(yv.y & 0xffff0000u);
;                         u32x2 w; w.x = cvt_pk_bf16(y0 * sigm(v[0]), y1 * sigm(v[1])); w.y = cvt_pk_bf16(y2 * sigm(v[2]), y3 * sigm(v[3]));
;                         *(u32x2*)(MIX + row * 1024 + 256 + c) = w;
	v_mul_f32_e32 v105, 0xbfb8aa3b, v105
	v_mul_f32_e32 v106, 0xbfb8aa3b, v106
	v_mul_f32_e32 v107, 0xbfb8aa3b, v107
	v_exp_f32_e32 v104, v104
	v_exp_f32_e32 v105, v105
	v_exp_f32_e32 v106, v106
	v_exp_f32_e32 v107, v107
	v_add_f32_e32 v104, 1.0, v104
	v_add_f32_e32 v105, 1.0, v105
	v_add_f32_e32 v106, 1.0, v106
	v_add_f32_e32 v107, 1.0, v107
	v_rcp_f32_e32 v104, v104
	v_rcp_f32_e32 v105, v105
	v_rcp_f32_e32 v106, v106
	v_rcp_f32_e32 v107, v107
	v_lshlrev_b32_e32 v153, 16, v170
	v_and_b32_e32 v170, 0xffff0000, v170
	v_lshlrev_b32_e32 v155, 16, v171
	v_and_b32_e32 v171, 0xffff0000, v171
	v_mul_f32_e32 v104, v104, v153
	v_mul_f32_e32 v105, v105, v170
	v_mul_f32_e32 v106, v106, v155
	v_mul_f32_e32 v107, v107, v171
	v_cvt_pk_bf16_f32 v104, v104, v105
	v_cvt_pk_bf16_f32 v105, v106, v107
	v_or_b32_e32 v152, 0x90, v154
	v_lshlrev_b32_e32 v220, 11, v152
	v_lshl_add_u64 v[150:151], v[142:143], 0, v[220:221]
	global_store_dwordx2 v[150:151], v[104:105], off offset:512
	v_pk_add_f32 v[100:101], v[100:101], v[128:129]
	v_pk_add_f32 v[102:103], v[102:103], v[130:131]
	v_mul_f32_e32 v100, 0xbfb8aa3b, v100
	v_mul_f32_e32 v101, 0xbfb8aa3b, v101
	v_mul_f32_e32 v102, 0xbfb8aa3b, v102
	v_mul_f32_e32 v103, 0xbfb8aa3b, v103
	v_exp_f32_e32 v100, v100
	v_exp_f32_e32 v101, v101
	v_exp_f32_e32 v102, v102
	v_exp_f32_e32 v103, v103
	v_add_f32_e32 v100, 1.0, v100
	v_add_f32_e32 v101, 1.0, v101
	v_add_f32_e32 v102, 1.0, v102
	v_add_f32_e32 v103, 1.0, v103
	v_rcp_f32_e32 v100, v100
	v_rcp_f32_e32 v101, v101
	v_rcp_f32_e32 v102, v102
	v_rcp_f32_e32 v103, v103
	v_lshlrev_b32_e32 v153, 16, v172
	v_and_b32_e32 v172, 0xffff0000, v172
	v_lshlrev_b32_e32 v155, 16, v173
	v_and_b32_e32 v173, 0xffff0000, v173
	v_mul_f32_e32 v100, v100, v153
	v_mul_f32_e32 v101, v101, v172
	v_mul_f32_e32 v102, v102, v155
	v_mul_f32_e32 v103, v103, v173
	v_cvt_pk_bf16_f32 v100, v100, v101
	v_cvt_pk_bf16_f32 v101, v102, v103
	v_or_b32_e32 v152, 0xa0, v154
	v_lshlrev_b32_e32 v220, 11, v152
	v_lshl_add_u64 v[150:151], v[142:143], 0, v[220:221]
	global_store_dwordx2 v[150:151], v[100:101], off offset:512
	v_pk_add_f32 v[96:97], v[96:97], v[128:129]
	v_pk_add_f32 v[98:99], v[98:99], v[130:131]
	v_mul_f32_e32 v96, 0xbfb8aa3b, v96
	v_mul_f32_e32 v97, 0xbfb8aa3b, v97
	v_mul_f32_e32 v98, 0xbfb8aa3b, v98
	v_mul_f32_e32 v99, 0xbfb8aa3b, v99
	v_exp_f32_e32 v96, v96
	v_exp_f32_e32 v97, v97
	v_exp_f32_e32 v98, v98
	v_exp_f32_e32 v99, v99
	v_add_f32_e32 v96, 1.0, v96
	v_add_f32_e32 v97, 1.0, v97
	v_add_f32_e32 v98, 1.0, v98
	v_add_f32_e32 v99, 1.0, v99
	v_rcp_f32_e32 v96, v96
	v_rcp_f32_e32 v97, v97
	v_rcp_f32_e32 v98, v98
	v_rcp_f32_e32 v99, v99
	v_lshlrev_b32_e32 v153, 16, v174
	v_and_b32_e32 v174, 0xffff0000, v174
	v_lshlrev_b32_e32 v155, 16, v175
	v_and_b32_e32 v175, 0xffff0000, v175
	v_mul_f32_e32 v96, v96, v153
	v_mul_f32_e32 v97, v97, v174
	v_mul_f32_e32 v98, v98, v155
	v_mul_f32_e32 v99, v99, v175
	v_cvt_pk_bf16_f32 v96, v96, v97
	v_cvt_pk_bf16_f32 v97, v98, v99
	v_or_b32_e32 v152, 0xb0, v154
	v_lshlrev_b32_e32 v220, 11, v152
	v_lshl_add_u64 v[150:151], v[142:143], 0, v[220:221]
	global_store_dwordx2 v[150:151], v[96:97], off offset:512
	global_load_dwordx4 v[96:99], v[138:139], off offset:512
	global_load_dwordx4 v[100:103], v[138:139], off offset:528
	v_lshlrev_b32_e32 v220, 9, v154
	v_lshl_add_u64 v[148:149], v[140:141], 0, v[220:221]
	global_load_dwordx2 v[104:105], v[148:149], off offset:264
	v_or_b32_e32 v152, 16, v154
	v_lshlrev_b32_e32 v220, 9, v152
	v_lshl_add_u64 v[148:149], v[140:141], 0, v[220:221]
	global_load_dwordx2 v[106:107], v[148:149], off offset:264
	v_or_b32_e32 v152, 32, v154
	v_lshlrev_b32_e32 v220, 9, v152
	v_lshl_add_u64 v[148:149], v[140:141], 0, v[220:221]
	global_load_dwordx2 v[108:109], v[148:149], off offset:264
	v_or_b32_e32 v152, 48, v154
	v_lshlrev_b32_e32 v220, 9, v152
	v_lshl_add_u64 v[148:149], v[140:141], 0, v[220:221]
	global_load_dwordx2 v[110:111], v[148:149], off offset:264
	v_or_b32_e32 v152, 0x80, v154
	v_lshlrev_b32_e32 v220, 9, v152
	v_lshl_add_u64 v[148:149], v[140:141], 0, v[220:221]
	global_load_dwordx2 v[112:113], v[148:149], off offset:264
	v_or_b32_e32 v152, 0x90, v154
	v_lshlrev_b32_e32 v220, 9, v152
	v_lshl_add_u64 v[148:149], v[140:141], 0, v[220:221]
	global_load_dwordx2 v[114:115], v[148:149], off offset:264
	v_or_b32_e32 v152, 0xa0, v154
	v_lshlrev_b32_e32 v220, 9, v152
	v_lshl_add_u64 v[148:149], v[140:141], 0, v[220:221]
	global_load_dwordx2 v[116:117], v[148:149], off offset:264
	v_or_b32_e32 v152, 0xb0, v154
	v_lshlrev_b32_e32 v220, 9, v152
	v_lshl_add_u64 v[148:149], v[140:141], 0, v[220:221]
	global_load_dwordx2 v[118:119], v[148:149], off offset:264
	s_waitcnt vmcnt(26)
; __device__ __forceinline__ unsigned cvt_pk_bf16(float lo, float hi) { unsigned r; asm volatile("v_cvt_pk_bf16_f32 %0, %1, %2" : "=v"(r) : "v"(lo), "v"(hi)); return r; }
; __device__ __forceinline__ float sigm(float v) { return __builtin_amdgcn_rcpf(1.0f + __builtin_amdgcn_exp2f(-1.4426950408889634f * v)); }
;     __device__ __forceinline__ void operator()(const f32x4 (&acc)[2][2][4][2], const Unit& u, int wr, int wc, int fr, int fq) const {
;     ...
;                 const f32x4 bv = *(const f32x4*)(bias + c);
; #pragma unroll
;                 for (int ai = 0; ai < 2; ++ai)
; #pragma unroll
;                     for (int m = 0; m < 4; ++m) {
;                         const size_t row = (size_t)(row0 + ai * HALF + m * 16);
;                         const f32x4 v = acc[ai][bj][m][n] + bv;
;                         const u32x2 yv = *(const u32x2*)(YGS + row * 256 + c);
;                         const float y0 = __uint_as_float(yv.x << 16), y1 = __uint_as_float(yv.x & 0xffff0000u), y2 = __uint_as_float(yv.y << 16), y3 = __uint_as_float(yv.y & 0xffff0000u);
;                         u32x2 w; w.x = cvt_pk_bf16(y0 * sigm(v[0]), y1 * sigm(v[1])); w.y = cvt_pk_bf16(y2 * sigm(v[2]), y3 * sigm(v[3]));
;                         *(u32x2*)(MIX + row * 1024 + 256 + c) = w;
;                         if (m & 1) asm volatile("" ::: "memory");
	v_pk_add_f32 v[92:93], v[92:93], v[208:209]
	v_pk_add_f32 v[94:95], v[94:95], v[210:211]
	v_mul_f32_e32 v92, 0xbfb8aa3b, v92
	v_mul_f32_e32 v93, 0xbfb8aa3b, v93
	v_mul_f32_e32 v94, 0xbfb8aa3b, v94
	v_mul_f32_e32 v95, 0xbfb8aa3b, v95
	v_exp_f32_e32 v92, v92
	v_exp_f32_e32 v93, v93
	v_exp_f32_e32 v94, v94
	v_exp_f32_e32 v95, v95
	v_add_f32_e32 v92, 1.0, v92
	v_add_f32_e32 v93, 1.0, v93
	v_add_f32_e32 v94, 1.0, v94
	v_add_f32_e32 v95, 1.0, v95
	v_rcp_f32_e32 v92, v92
	v_rcp_f32_e32 v93, v93
	v_rcp_f32_e32 v94, v94
	v_rcp_f32_e32 v95, v95
	v_lshlrev_b32_e32 v153, 16, v176
	v_and_b32_e32 v176, 0xffff0000, v176
	v_lshlrev_b32_e32 v155, 16, v177
	v_and_b32_e32 v177, 0xffff0000, v177
	v_mul_f32_e32 v92, v92, v153
	v_mul_f32_e32 v93, v93, v176
	v_mul_f32_e32 v94, v94, v155
	v_mul_f32_e32 v95, v95, v177
	v_cvt_pk_bf16_f32 v92, v92, v93
	v_cvt_pk_bf16_f32 v93, v94, v95
	v_lshlrev_b32_e32 v220, 11, v154
	v_lshl_add_u64 v[150:151], v[142:143], 0, v[220:221]
	global_store_dwordx2 v[150:151], v[92:93], off offset:520
	v_pk_add_f32 v[88:89], v[88:89], v[208:209]
	v_pk_add_f32 v[90:91], v[90:91], v[210:211]
	v_mul_f32_e32 v88, 0xbfb8aa3b, v88
	v_mul_f32_e32 v89, 0xbfb8aa3b, v89
	v_mul_f32_e32 v90, 0xbfb8aa3b, v90
	v_mul_f32_e32 v91, 0xbfb8aa3b, v91
	v_exp_f32_e32 v88, v88
	v_exp_f32_e32 v89, v89
	v_exp_f32_e32 v90, v90
	v_exp_f32_e32 v91, v91
	v_add_f32_e32 v88, 1.0, v88
	v_add_f32_e32 v89, 1.0, v89
	v_add_f32_e32 v90, 1.0, v90
	v_add_f32_e32 v91, 1.0, v91
	v_rcp_f32_e32 v88, v88
	v_rcp_f32_e32 v89, v89
	v_rcp_f32_e32 v90, v90
	v_rcp_f32_e32 v91, v91
	v_lshlrev_b32_e32 v153, 16, v178
	v_and_b32_e32 v178, 0xffff0000, v178
	v_lshlrev_b32_e32 v155, 16, v179
	v_and_b32_e32 v179, 0xffff0000, v179
	v_mul_f32_e32 v88, v88, v153
	v_mul_f32_e32 v89, v89, v178
	v_mul_f32_e32 v90, v90, v155
	v_mul_f32_e32 v91, v91, v179
	v_cvt_pk_bf16_f32 v88, v88, v89
	v_cvt_pk_bf16_f32 v89, v90, v91
	v_or_b32_e32 v152, 16, v154
	v_lshlrev_b32_e32 v220, 11, v152
	v_lshl_add_u64 v[150:151], v[142:143], 0, v[220:221]
	global_store_dwordx2 v[150:151], v[88:89], off offset:520
	v_pk_add_f32 v[84:85], v[84:85], v[208:209]
	v_pk_add_f32 v[86:87], v[86:87], v[210:211]
	v_mul_f32_e32 v84, 0xbfb8aa3b, v84
	v_mul_f32_e32 v85, 0xbfb8aa3b, v85
	v_mul_f32_e32 v86, 0xbfb8aa3b, v86
	v_mul_f32_e32 v87, 0xbfb8aa3b, v87
	v_exp_f32_e32 v84, v84
	v_exp_f32_e32 v85, v85
	v_exp_f32_e32 v86, v86
	v_exp_f32_e32 v87, v87
	v_add_f32_e32 v84, 1.0, v84
	v_add_f32_e32 v85, 1.0, v85
	v_add_f32_e32 v86, 1.0, v86
	v_add_f32_e32 v87, 1.0, v87
	v_rcp_f32_e32 v84, v84
	v_rcp_f32_e32 v85, v85
	v_rcp_f32_e32 v86, v86
	v_rcp_f32_e32 v87, v87
	v_lshlrev_b32_e32 v153, 16, v180
	v_and_b32_e32 v180, 0xffff0000, v180
	v_lshlrev_b32_e32 v155, 16, v181
	v_and_b32_e32 v181, 0xffff0000, v181
	v_mul_f32_e32 v84, v84, v153
	v_mul_f32_e32 v85, v85, v180
	v_mul_f32_e32 v86, v86, v155
	v_mul_f32_e32 v87, v87, v181
	v_cvt_pk_bf16_f32 v84, v84, v85
	v_cvt_pk_bf16_f32 v85, v86, v87
	v_or_b32_e32 v152, 32, v154
	v_lshlrev_b32_e32 v220, 11, v152
	v_lshl_add_u64 v[150:151], v[142:143], 0, v[220:221]
	global_store_dwordx2 v[150:151], v[84:85], off offset:520
	v_pk_add_f32 v[80:81], v[80:81], v[208:209]
	v_pk_add_f32 v[82:83], v[82:83], v[210:211]
	v_mul_f32_e32 v80, 0xbfb8aa3b, v80
	v_mul_f32_e32 v81, 0xbfb8aa3b, v81
	v_mul_f32_e32 v82, 0xbfb8aa3b, v82
	v_mul_f32_e32 v83, 0xbfb8aa3b, v83
	v_exp_f32_e32 v80, v80
	v_exp_f32_e32 v81, v81
	v_exp_f32_e32 v82, v82
	v_exp_f32_e32 v83, v83
	v_add_f32_e32 v80, 1.0, v80
	v_add_f32_e32 v81, 1.0, v81
	v_add_f32_e32 v82, 1.0, v82
	v_add_f32_e32 v83, 1.0, v83
	v_rcp_f32_e32 v80, v80
	v_rcp_f32_e32 v81, v81
	v_rcp_f32_e32 v82, v82
	v_rcp_f32_e32 v83, v83
	v_lshlrev_b32_e32 v153, 16, v182
	v_and_b32_e32 v182, 0xffff0000, v182
	v_lshlrev_b32_e32 v155, 16, v183
	v_and_b32_e32 v183, 0xffff0000, v183
	v_mul_f32_e32 v80, v80, v153
	v_mul_f32_e32 v81, v81, v182
	v_mul_f32_e32 v82, v82, v155
	v_mul_f32_e32 v83, v83, v183
	v_cvt_pk_bf16_f32 v80, v80, v81
	v_cvt_pk_bf16_f32 v81, v82, v83
	v_or_b32_e32 v152, 48, v154
	v_lshlrev_b32_e32 v220, 11, v152
	v_lshl_add_u64 v[150:151], v[142:143], 0, v[220:221]
	global_store_dwordx2 v[150:151], v[80:81], off offset:520
	v_pk_add_f32 v[76:77], v[76:77], v[208:209]
	v_pk_add_f32 v[78:79], v[78:79], v[210:211]
	v_mul_f32_e32 v76, 0xbfb8aa3b, v76
	v_mul_f32_e32 v77, 0xbfb8aa3b, v77
	v_mul_f32_e32 v78, 0xbfb8aa3b, v78
	v_mul_f32_e32 v79, 0xbfb8aa3b, v79
	v_exp_f32_e32 v76, v76
	v_exp_f32_e32 v77, v77
	v_exp_f32_e32 v78, v78
	v_exp_f32_e32 v79, v79
	v_add_f32_e32 v76, 1.0, v76
	v_add_f32_e32 v77, 1.0, v77
	v_add_f32_e32 v78, 1.0, v78
	v_add_f32_e32 v79, 1.0, v79
	v_rcp_f32_e32 v76, v76
	v_rcp_f32_e32 v77, v77
	v_rcp_f32_e32 v78, v78
	v_rcp_f32_e32 v79, v79
	v_lshlrev_b32_e32 v153, 16, v184
	v_and_b32_e32 v184, 0xffff0000, v184
	v_lshlrev_b32_e32 v155, 16, v185
	v_and_b32_e32 v185, 0xffff0000, v185
	v_mul_f32_e32 v76, v76, v153
	v_mul_f32_e32 v77, v77, v184
	v_mul_f32_e32 v78, v78, v155
	v_mul_f32_e32 v79, v79, v185
	v_cvt_pk_bf16_f32 v76, v76, v77
	v_cvt_pk_bf16_f32 v77, v78, v79
	v_or_b32_e32 v152, 0x80, v154
	v_lshlrev_b32_e32 v220, 11, v152
	v_lshl_add_u64 v[150:151], v[142:143], 0, v[220:221]
	global_store_dwordx2 v[150:151], v[76:77], off offset:520
	v_pk_add_f32 v[72:73], v[72:73], v[208:209]
	v_pk_add_f32 v[74:75], v[74:75], v[210:211]
	v_mul_f32_e32 v72, 0xbfb8aa3b, v72
	v_mul_f32_e32 v73, 0xbfb8aa3b, v73
	v_mul_f32_e32 v74, 0xbfb8aa3b, v74
	v_mul_f32_e32 v75, 0xbfb8aa3b, v75
	v_exp_f32_e32 v72, v72
	v_exp_f32_e32 v73, v73
	v_exp_f32_e32 v74, v74
	v_exp_f32_e32 v75, v75
	v_add_f32_e32 v72, 1.0, v72
	v_add_f32_e32 v73, 1.0, v73
	v_add_f32_e32 v74, 1.0, v74
; __device__ __forceinline__ unsigned cvt_pk_bf16(float lo, float hi) { unsigned r; asm volatile("v_cvt_pk_bf16_f32 %0, %1, %2" : "=v"(r) : "v"(lo), "v"(hi)); return r; }
; __device__ __forceinline__ float sigm(float v) { return __builtin_amdgcn_rcpf(1.0f + __builtin_amdgcn_exp2f(-1.4426950408889634f * v)); }
;     __device__ __forceinline__ void operator()(const f32x4 (&acc)[2][2][4][2], const Unit& u, int wr, int wc, int fr, int fq) const {
;     ...
;                 const f32x4 bv = *(const f32x4*)(bias + c);
; #pragma unroll
;                 for (int ai = 0; ai < 2; ++ai)
; #pragma unroll
;                     for (int m = 0; m < 4; ++m) {
;                         const size_t row = (size_t)(row0 + ai * HALF + m * 16);
;                         const f32x4 v = acc[ai][bj][m][n] + bv;
;                         const u32x2 yv = *(const u32x2*)(YGS + row * 256 + c);
;                         const float y0 = __uint_as_float(yv.x << 16), y1 = __uint_as_float(yv.x & 0xffff0000u), y2 = __uint_as_float(yv.y << 16), y3 = __uint_as_float(yv.y & 0xffff0000u);
;                         u32x2 w; w.x = cvt_pk_bf16(y0 * sigm(v[0]), y1 * sigm(v[1])); w.y = cvt_pk_bf16(y2 * sigm(v[2]), y3 * sigm(v[3]));
;                         *(u32x2*)(MIX + row * 1024 + 256 + c) = w;
;                         if (m & 1) asm volatile("" ::: "memory");
	v_add_f32_e32 v75, 1.0, v75
	v_rcp_f32_e32 v72, v72
	v_rcp_f32_e32 v73, v73
	v_rcp_f32_e32 v74, v74
	v_rcp_f32_e32 v75, v75
	v_lshlrev_b32_e32 v153, 16, v186
	v_and_b32_e32 v186, 0xffff0000, v186
	v_lshlrev_b32_e32 v155, 16, v187
	v_and_b32_e32 v187, 0xffff0000, v187
	v_mul_f32_e32 v72, v72, v153
	v_mul_f32_e32 v73, v73, v186
	v_mul_f32_e32 v74, v74, v155
	v_mul_f32_e32 v75, v75, v187
	v_cvt_pk_bf16_f32 v72, v72, v73
	v_cvt_pk_bf16_f32 v73, v74, v75
	v_or_b32_e32 v152, 0x90, v154
	v_lshlrev_b32_e32 v220, 11, v152
	v_lshl_add_u64 v[150:151], v[142:143], 0, v[220:221]
	global_store_dwordx2 v[150:151], v[72:73], off offset:520
	v_pk_add_f32 v[68:69], v[68:69], v[208:209]
	v_pk_add_f32 v[70:71], v[70:71], v[210:211]
	v_mul_f32_e32 v68, 0xbfb8aa3b, v68
	v_mul_f32_e32 v69, 0xbfb8aa3b, v69
	v_mul_f32_e32 v70, 0xbfb8aa3b, v70
	v_mul_f32_e32 v71, 0xbfb8aa3b, v71
	v_exp_f32_e32 v68, v68
	v_exp_f32_e32 v69, v69
	v_exp_f32_e32 v70, v70
	v_exp_f32_e32 v71, v71
	v_add_f32_e32 v68, 1.0, v68
	v_add_f32_e32 v69, 1.0, v69
	v_add_f32_e32 v70, 1.0, v70
	v_add_f32_e32 v71, 1.0, v71
	v_rcp_f32_e32 v68, v68
	v_rcp_f32_e32 v69, v69
	v_rcp_f32_e32 v70, v70
	v_rcp_f32_e32 v71, v71
	v_lshlrev_b32_e32 v153, 16, v188
	v_and_b32_e32 v188, 0xffff0000, v188
	v_lshlrev_b32_e32 v155, 16, v189
	v_and_b32_e32 v189, 0xffff0000, v189
	v_mul_f32_e32 v68, v68, v153
	v_mul_f32_e32 v69, v69, v188
	v_mul_f32_e32 v70, v70, v155
	v_mul_f32_e32 v71, v71, v189
	v_cvt_pk_bf16_f32 v68, v68, v69
	v_cvt_pk_bf16_f32 v69, v70, v71
	v_or_b32_e32 v152, 0xa0, v154
	v_lshlrev_b32_e32 v220, 11, v152
	v_lshl_add_u64 v[150:151], v[142:143], 0, v[220:221]
	global_store_dwordx2 v[150:151], v[68:69], off offset:520
	v_pk_add_f32 v[64:65], v[64:65], v[208:209]
	v_pk_add_f32 v[66:67], v[66:67], v[210:211]
	v_mul_f32_e32 v64, 0xbfb8aa3b, v64
	v_mul_f32_e32 v65, 0xbfb8aa3b, v65
	v_mul_f32_e32 v66, 0xbfb8aa3b, v66
	v_mul_f32_e32 v67, 0xbfb8aa3b, v67
	v_exp_f32_e32 v64, v64
	v_exp_f32_e32 v65, v65
	v_exp_f32_e32 v66, v66
	v_exp_f32_e32 v67, v67
	v_add_f32_e32 v64, 1.0, v64
	v_add_f32_e32 v65, 1.0, v65
	v_add_f32_e32 v66, 1.0, v66
	v_add_f32_e32 v67, 1.0, v67
	v_rcp_f32_e32 v64, v64
	v_rcp_f32_e32 v65, v65
	v_rcp_f32_e32 v66, v66
	v_rcp_f32_e32 v67, v67
	v_lshlrev_b32_e32 v153, 16, v190
	v_and_b32_e32 v190, 0xffff0000, v190
	v_lshlrev_b32_e32 v155, 16, v191
	v_and_b32_e32 v191, 0xffff0000, v191
	v_mul_f32_e32 v64, v64, v153
	v_mul_f32_e32 v65, v65, v190
	v_mul_f32_e32 v66, v66, v155
	v_mul_f32_e32 v67, v67, v191
	v_cvt_pk_bf16_f32 v64, v64, v65
	v_cvt_pk_bf16_f32 v65, v66, v67
	v_or_b32_e32 v152, 0xb0, v154
	v_lshlrev_b32_e32 v220, 11, v152
	v_lshl_add_u64 v[150:151], v[142:143], 0, v[220:221]
	global_store_dwordx2 v[150:151], v[64:65], off offset:520
	s_waitcnt vmcnt(17)
	v_pk_add_f32 v[60:61], v[60:61], v[96:97]
	v_pk_add_f32 v[62:63], v[62:63], v[98:99]
	v_mul_f32_e32 v60, 0xbfb8aa3b, v60
	v_mul_f32_e32 v61, 0xbfb8aa3b, v61
	v_mul_f32_e32 v62, 0xbfb8aa3b, v62
	v_mul_f32_e32 v63, 0xbfb8aa3b, v63
	v_exp_f32_e32 v60, v60
	v_exp_f32_e32 v61, v61
	v_exp_f32_e32 v62, v62
	v_exp_f32_e32 v63, v63
	v_add_f32_e32 v60, 1.0, v60
	v_add_f32_e32 v61, 1.0, v61
	v_add_f32_e32 v62, 1.0, v62
	v_add_f32_e32 v63, 1.0, v63
	v_rcp_f32_e32 v60, v60
	v_rcp_f32_e32 v61, v61
	v_rcp_f32_e32 v62, v62
	v_rcp_f32_e32 v63, v63
	v_lshlrev_b32_e32 v153, 16, v192
	v_and_b32_e32 v192, 0xffff0000, v192
	v_lshlrev_b32_e32 v155, 16, v193
	v_and_b32_e32 v193, 0xffff0000, v193
	v_mul_f32_e32 v60, v60, v153
	v_mul_f32_e32 v61, v61, v192
	v_mul_f32_e32 v62, v62, v155
	v_mul_f32_e32 v63, v63, v193
	v_cvt_pk_bf16_f32 v60, v60, v61
	v_cvt_pk_bf16_f32 v61, v62, v63
	v_lshlrev_b32_e32 v220, 11, v154
	v_lshl_add_u64 v[150:151], v[142:143], 0, v[220:221]
	global_store_dwordx2 v[150:151], v[60:61], off offset:768
	v_pk_add_f32 v[56:57], v[56:57], v[96:97]
	v_pk_add_f32 v[58:59], v[58:59], v[98:99]
	v_mul_f32_e32 v56, 0xbfb8aa3b, v56
	v_mul_f32_e32 v57, 0xbfb8aa3b, v57
	v_mul_f32_e32 v58, 0xbfb8aa3b, v58
	v_mul_f32_e32 v59, 0xbfb8aa3b, v59
	v_exp_f32_e32 v56, v56
	v_exp_f32_e32 v57, v57
	v_exp_f32_e32 v58, v58
	v_exp_f32_e32 v59, v59
	v_add_f32_e32 v56, 1.0, v56
	v_add_f32_e32 v57, 1.0, v57
	v_add_f32_e32 v58, 1.0, v58
	v_add_f32_e32 v59, 1.0, v59
	v_rcp_f32_e32 v56, v56
	v_rcp_f32_e32 v57, v57
	v_rcp_f32_e32 v58, v58
	v_rcp_f32_e32 v59, v59
	v_lshlrev_b32_e32 v153, 16, v194
	v_and_b32_e32 v194, 0xffff0000, v194
	v_lshlrev_b32_e32 v155, 16, v195
	v_and_b32_e32 v195, 0xffff0000, v195
	v_mul_f32_e32 v56, v56, v153
	v_mul_f32_e32 v57, v57, v194
	v_mul_f32_e32 v58, v58, v155
	v_mul_f32_e32 v59, v59, v195
	v_cvt_pk_bf16_f32 v56, v56, v57
	v_cvt_pk_bf16_f32 v57, v58, v59
	v_or_b32_e32 v152, 16, v154
	v_lshlrev_b32_e32 v220, 11, v152
	v_lshl_add_u64 v[150:151], v[142:143], 0, v[220:221]
	global_store_dwordx2 v[150:151], v[56:57], off offset:768
	v_pk_add_f32 v[52:53], v[52:53], v[96:97]
	v_pk_add_f32 v[54:55], v[54:55], v[98:99]
	v_mul_f32_e32 v52, 0xbfb8aa3b, v52
	v_mul_f32_e32 v53, 0xbfb8aa3b, v53
	v_mul_f32_e32 v54, 0xbfb8aa3b, v54
	v_mul_f32_e32 v55, 0xbfb8aa3b, v55
	v_exp_f32_e32 v52, v52
	v_exp_f32_e32 v53, v53
	v_exp_f32_e32 v54, v54
	v_exp_f32_e32 v55, v55
	v_add_f32_e32 v52, 1.0, v52
	v_add_f32_e32 v53, 1.0, v53
	v_add_f32_e32 v54, 1.0, v54
	v_add_f32_e32 v55, 1.0, v55
	v_rcp_f32_e32 v52, v52
	v_rcp_f32_e32 v53, v53
	v_rcp_f32_e32 v54, v54
	v_rcp_f32_e32 v55, v55
	v_lshlrev_b32_e32 v153, 16, v196
	v_and_b32_e32 v196, 0xffff0000, v196
	v_lshlrev_b32_e32 v155, 16, v197
	v_and_b32_e32 v197, 0xffff0000, v197
	v_mul_f32_e32 v52, v52, v153
	v_mul_f32_e32 v53, v53, v196
	v_mul_f32_e32 v54, v54, v155
	v_mul_f32_e32 v55, v55, v197
	v_cvt_pk_bf16_f32 v52, v52, v53
; __device__ __forceinline__ unsigned cvt_pk_bf16(float lo, float hi) { unsigned r; asm volatile("v_cvt_pk_bf16_f32 %0, %1, %2" : "=v"(r) : "v"(lo), "v"(hi)); return r; }
; __device__ __forceinline__ float sigm(float v) { return __builtin_amdgcn_rcpf(1.0f + __builtin_amdgcn_exp2f(-1.4426950408889634f * v)); }
;     __device__ __forceinline__ void operator()(const f32x4 (&acc)[2][2][4][2], const Unit& u, int wr, int wc, int fr, int fq) const {
;     ...
;                 const f32x4 bv = *(const f32x4*)(bias + c);
; #pragma unroll
;                 for (int ai = 0; ai < 2; ++ai)
; #pragma unroll
;                     for (int m = 0; m < 4; ++m) {
;                         const size_t row = (size_t)(row0 + ai * HALF + m * 16);
;                         const f32x4 v = acc[ai][bj][m][n] + bv;
;                         const u32x2 yv = *(const u32x2*)(YGS + row * 256 + c);
;                         const float y0 = __uint_as_float(yv.x << 16), y1 = __uint_as_float(yv.x & 0xffff0000u), y2 = __uint_as_float(yv.y << 16), y3 = __uint_as_float(yv.y & 0xffff0000u);
;                         u32x2 w; w.x = cvt_pk_bf16(y0 * sigm(v[0]), y1 * sigm(v[1])); w.y = cvt_pk_bf16(y2 * sigm(v[2]), y3 * sigm(v[3]));
;                         *(u32x2*)(MIX + row * 1024 + 256 + c) = w;
;                         if (m & 1) asm volatile("" ::: "memory");
	v_cvt_pk_bf16_f32 v53, v54, v55
	v_or_b32_e32 v152, 32, v154
	v_lshlrev_b32_e32 v220, 11, v152
	v_lshl_add_u64 v[150:151], v[142:143], 0, v[220:221]
	global_store_dwordx2 v[150:151], v[52:53], off offset:768
	v_pk_add_f32 v[48:49], v[48:49], v[96:97]
	v_pk_add_f32 v[50:51], v[50:51], v[98:99]
	v_mul_f32_e32 v48, 0xbfb8aa3b, v48
	v_mul_f32_e32 v49, 0xbfb8aa3b, v49
	v_mul_f32_e32 v50, 0xbfb8aa3b, v50
	v_mul_f32_e32 v51, 0xbfb8aa3b, v51
	v_exp_f32_e32 v48, v48
	v_exp_f32_e32 v49, v49
	v_exp_f32_e32 v50, v50
	v_exp_f32_e32 v51, v51
	v_add_f32_e32 v48, 1.0, v48
	v_add_f32_e32 v49, 1.0, v49
	v_add_f32_e32 v50, 1.0, v50
	v_add_f32_e32 v51, 1.0, v51
	v_rcp_f32_e32 v48, v48
	v_rcp_f32_e32 v49, v49
	v_rcp_f32_e32 v50, v50
	v_rcp_f32_e32 v51, v51
	v_lshlrev_b32_e32 v153, 16, v198
	v_and_b32_e32 v198, 0xffff0000, v198
	v_lshlrev_b32_e32 v155, 16, v199
	v_and_b32_e32 v199, 0xffff0000, v199
	v_mul_f32_e32 v48, v48, v153
	v_mul_f32_e32 v49, v49, v198
	v_mul_f32_e32 v50, v50, v155
	v_mul_f32_e32 v51, v51, v199
	v_cvt_pk_bf16_f32 v48, v48, v49
	v_cvt_pk_bf16_f32 v49, v50, v51
	v_or_b32_e32 v152, 48, v154
	v_lshlrev_b32_e32 v220, 11, v152
	v_lshl_add_u64 v[150:151], v[142:143], 0, v[220:221]
	global_store_dwordx2 v[150:151], v[48:49], off offset:768
	v_pk_add_f32 v[44:45], v[44:45], v[96:97]
	v_pk_add_f32 v[46:47], v[46:47], v[98:99]
	v_mul_f32_e32 v44, 0xbfb8aa3b, v44
	v_mul_f32_e32 v45, 0xbfb8aa3b, v45
	v_mul_f32_e32 v46, 0xbfb8aa3b, v46
	v_mul_f32_e32 v47, 0xbfb8aa3b, v47
	v_exp_f32_e32 v44, v44
	v_exp_f32_e32 v45, v45
	v_exp_f32_e32 v46, v46
	v_exp_f32_e32 v47, v47
	v_add_f32_e32 v44, 1.0, v44
	v_add_f32_e32 v45, 1.0, v45
	v_add_f32_e32 v46, 1.0, v46
	v_add_f32_e32 v47, 1.0, v47
	v_rcp_f32_e32 v44, v44
	v_rcp_f32_e32 v45, v45
	v_rcp_f32_e32 v46, v46
	v_rcp_f32_e32 v47, v47
	v_lshlrev_b32_e32 v153, 16, v200
	v_and_b32_e32 v200, 0xffff0000, v200
	v_lshlrev_b32_e32 v155, 16, v201
	v_and_b32_e32 v201, 0xffff0000, v201
	v_mul_f32_e32 v44, v44, v153
	v_mul_f32_e32 v45, v45, v200
	v_mul_f32_e32 v46, v46, v155
	v_mul_f32_e32 v47, v47, v201
	v_cvt_pk_bf16_f32 v44, v44, v45
	v_cvt_pk_bf16_f32 v45, v46, v47
	v_or_b32_e32 v152, 0x80, v154
	v_lshlrev_b32_e32 v220, 11, v152
	v_lshl_add_u64 v[150:151], v[142:143], 0, v[220:221]
	global_store_dwordx2 v[150:151], v[44:45], off offset:768
	v_pk_add_f32 v[40:41], v[40:41], v[96:97]
	v_pk_add_f32 v[42:43], v[42:43], v[98:99]
	v_mul_f32_e32 v40, 0xbfb8aa3b, v40
	v_mul_f32_e32 v41, 0xbfb8aa3b, v41
	v_mul_f32_e32 v42, 0xbfb8aa3b, v42
	v_mul_f32_e32 v43, 0xbfb8aa3b, v43
	v_exp_f32_e32 v40, v40
	v_exp_f32_e32 v41, v41
	v_exp_f32_e32 v42, v42
	v_exp_f32_e32 v43, v43
	v_add_f32_e32 v40, 1.0, v40
	v_add_f32_e32 v41, 1.0, v41
	v_add_f32_e32 v42, 1.0, v42
	v_add_f32_e32 v43, 1.0, v43
	v_rcp_f32_e32 v40, v40
	v_rcp_f32_e32 v41, v41
	v_rcp_f32_e32 v42, v42
	v_rcp_f32_e32 v43, v43
	v_lshlrev_b32_e32 v153, 16, v202
	v_and_b32_e32 v202, 0xffff0000, v202
	v_lshlrev_b32_e32 v155, 16, v203
	v_and_b32_e32 v203, 0xffff0000, v203
	v_mul_f32_e32 v40, v40, v153
	v_mul_f32_e32 v41, v41, v202
	v_mul_f32_e32 v42, v42, v155
	v_mul_f32_e32 v43, v43, v203
	v_cvt_pk_bf16_f32 v40, v40, v41
	v_cvt_pk_bf16_f32 v41, v42, v43
	v_or_b32_e32 v152, 0x90, v154
	v_lshlrev_b32_e32 v220, 11, v152
	v_lshl_add_u64 v[150:151], v[142:143], 0, v[220:221]
	global_store_dwordx2 v[150:151], v[40:41], off offset:768
	v_pk_add_f32 v[36:37], v[36:37], v[96:97]
	v_pk_add_f32 v[38:39], v[38:39], v[98:99]
	v_mul_f32_e32 v36, 0xbfb8aa3b, v36
	v_mul_f32_e32 v37, 0xbfb8aa3b, v37
	v_mul_f32_e32 v38, 0xbfb8aa3b, v38
	v_mul_f32_e32 v39, 0xbfb8aa3b, v39
	v_exp_f32_e32 v36, v36
	v_exp_f32_e32 v37, v37
	v_exp_f32_e32 v38, v38
	v_exp_f32_e32 v39, v39
	v_add_f32_e32 v36, 1.0, v36
	v_add_f32_e32 v37, 1.0, v37
	v_add_f32_e32 v38, 1.0, v38
	v_add_f32_e32 v39, 1.0, v39
	v_rcp_f32_e32 v36, v36
	v_rcp_f32_e32 v37, v37
	v_rcp_f32_e32 v38, v38
	v_rcp_f32_e32 v39, v39
	v_lshlrev_b32_e32 v153, 16, v204
	v_and_b32_e32 v204, 0xffff0000, v204
	v_lshlrev_b32_e32 v155, 16, v205
	v_and_b32_e32 v205, 0xffff0000, v205
	v_mul_f32_e32 v36, v36, v153
	v_mul_f32_e32 v37, v37, v204
	v_mul_f32_e32 v38, v38, v155
	v_mul_f32_e32 v39, v39, v205
	v_cvt_pk_bf16_f32 v36, v36, v37
	v_cvt_pk_bf16_f32 v37, v38, v39
	v_or_b32_e32 v152, 0xa0, v154
	v_lshlrev_b32_e32 v220, 11, v152
	v_lshl_add_u64 v[150:151], v[142:143], 0, v[220:221]
	global_store_dwordx2 v[150:151], v[36:37], off offset:768
	v_pk_add_f32 v[32:33], v[32:33], v[96:97]
	v_pk_add_f32 v[34:35], v[34:35], v[98:99]
	v_mul_f32_e32 v32, 0xbfb8aa3b, v32
	v_mul_f32_e32 v33, 0xbfb8aa3b, v33
	v_mul_f32_e32 v34, 0xbfb8aa3b, v34
	v_mul_f32_e32 v35, 0xbfb8aa3b, v35
	v_exp_f32_e32 v32, v32
	v_exp_f32_e32 v33, v33
	v_exp_f32_e32 v34, v34
	v_exp_f32_e32 v35, v35
	v_add_f32_e32 v32, 1.0, v32
	v_add_f32_e32 v33, 1.0, v33
	v_add_f32_e32 v34, 1.0, v34
	v_add_f32_e32 v35, 1.0, v35
	v_rcp_f32_e32 v32, v32
	v_rcp_f32_e32 v33, v33
	v_rcp_f32_e32 v34, v34
	v_rcp_f32_e32 v35, v35
	v_lshlrev_b32_e32 v153, 16, v206
	v_and_b32_e32 v206, 0xffff0000, v206
	v_lshlrev_b32_e32 v155, 16, v207
	v_and_b32_e32 v207, 0xffff0000, v207
	v_mul_f32_e32 v32, v32, v153
	v_mul_f32_e32 v33, v33, v206
	v_mul_f32_e32 v34, v34, v155
	v_mul_f32_e32 v35, v35, v207
	v_cvt_pk_bf16_f32 v32, v32, v33
	v_cvt_pk_bf16_f32 v33, v34, v35
	v_or_b32_e32 v152, 0xb0, v154
	v_lshlrev_b32_e32 v220, 11, v152
	v_lshl_add_u64 v[150:151], v[142:143], 0, v[220:221]
	global_store_dwordx2 v[150:151], v[32:33], off offset:768
	s_waitcnt vmcnt(16)
; __device__ __forceinline__ unsigned cvt_pk_bf16(float lo, float hi) { unsigned r; asm volatile("v_cvt_pk_bf16_f32 %0, %1, %2" : "=v"(r) : "v"(lo), "v"(hi)); return r; }
; __device__ __forceinline__ float sigm(float v) { return __builtin_amdgcn_rcpf(1.0f + __builtin_amdgcn_exp2f(-1.4426950408889634f * v)); }
;     __device__ __forceinline__ void operator()(const f32x4 (&acc)[2][2][4][2], const Unit& u, int wr, int wc, int fr, int fq) const {
;     ...
;                 const f32x4 bv = *(const f32x4*)(bias + c);
; #pragma unroll
;                 for (int ai = 0; ai < 2; ++ai)
; #pragma unroll
;                     for (int m = 0; m < 4; ++m) {
;                         const size_t row = (size_t)(row0 + ai * HALF + m * 16);
;                         const f32x4 v = acc[ai][bj][m][n] + bv;
;                         const u32x2 yv = *(const u32x2*)(YGS + row * 256 + c);
;                         const float y0 = __uint_as_float(yv.x << 16), y1 = __uint_as_float(yv.x & 0xffff0000u), y2 = __uint_as_float(yv.y << 16), y3 = __uint_as_float(yv.y & 0xffff0000u);
;                         u32x2 w; w.x = cvt_pk_bf16(y0 * sigm(v[0]), y1 * sigm(v[1])); w.y = cvt_pk_bf16(y2 * sigm(v[2]), y3 * sigm(v[3]));
;                         *(u32x2*)(MIX + row * 1024 + 256 + c) = w;
;                         if (m & 1) asm volatile("" ::: "memory");
	v_pk_add_f32 v[28:29], v[28:29], v[100:101]
	v_pk_add_f32 v[30:31], v[30:31], v[102:103]
	v_mul_f32_e32 v28, 0xbfb8aa3b, v28
	v_mul_f32_e32 v29, 0xbfb8aa3b, v29
	v_mul_f32_e32 v30, 0xbfb8aa3b, v30
	v_mul_f32_e32 v31, 0xbfb8aa3b, v31
	v_exp_f32_e32 v28, v28
	v_exp_f32_e32 v29, v29
	v_exp_f32_e32 v30, v30
	v_exp_f32_e32 v31, v31
	v_add_f32_e32 v28, 1.0, v28
	v_add_f32_e32 v29, 1.0, v29
	v_add_f32_e32 v30, 1.0, v30
	v_add_f32_e32 v31, 1.0, v31
	v_rcp_f32_e32 v28, v28
	v_rcp_f32_e32 v29, v29
	v_rcp_f32_e32 v30, v30
	v_rcp_f32_e32 v31, v31
	v_lshlrev_b32_e32 v153, 16, v104
	v_and_b32_e32 v104, 0xffff0000, v104
	v_lshlrev_b32_e32 v155, 16, v105
	v_and_b32_e32 v105, 0xffff0000, v105
	v_mul_f32_e32 v28, v28, v153
	v_mul_f32_e32 v29, v29, v104
	v_mul_f32_e32 v30, v30, v155
	v_mul_f32_e32 v31, v31, v105
	v_cvt_pk_bf16_f32 v28, v28, v29
	v_cvt_pk_bf16_f32 v29, v30, v31
	v_lshlrev_b32_e32 v220, 11, v154
	v_lshl_add_u64 v[150:151], v[142:143], 0, v[220:221]
	global_store_dwordx2 v[150:151], v[28:29], off offset:776
	v_pk_add_f32 v[24:25], v[24:25], v[100:101]
	v_pk_add_f32 v[26:27], v[26:27], v[102:103]
	v_mul_f32_e32 v24, 0xbfb8aa3b, v24
	v_mul_f32_e32 v25, 0xbfb8aa3b, v25
	v_mul_f32_e32 v26, 0xbfb8aa3b, v26
	v_mul_f32_e32 v27, 0xbfb8aa3b, v27
	v_exp_f32_e32 v24, v24
	v_exp_f32_e32 v25, v25
	v_exp_f32_e32 v26, v26
	v_exp_f32_e32 v27, v27
	v_add_f32_e32 v24, 1.0, v24
	v_add_f32_e32 v25, 1.0, v25
	v_add_f32_e32 v26, 1.0, v26
	v_add_f32_e32 v27, 1.0, v27
	v_rcp_f32_e32 v24, v24
	v_rcp_f32_e32 v25, v25
	v_rcp_f32_e32 v26, v26
	v_rcp_f32_e32 v27, v27
	v_lshlrev_b32_e32 v153, 16, v106
	v_and_b32_e32 v106, 0xffff0000, v106
	v_lshlrev_b32_e32 v155, 16, v107
	v_and_b32_e32 v107, 0xffff0000, v107
	v_mul_f32_e32 v24, v24, v153
	v_mul_f32_e32 v25, v25, v106
	v_mul_f32_e32 v26, v26, v155
	v_mul_f32_e32 v27, v27, v107
	v_cvt_pk_bf16_f32 v24, v24, v25
	v_cvt_pk_bf16_f32 v25, v26, v27
	v_or_b32_e32 v152, 16, v154
	v_lshlrev_b32_e32 v220, 11, v152
	v_lshl_add_u64 v[150:151], v[142:143], 0, v[220:221]
	global_store_dwordx2 v[150:151], v[24:25], off offset:776
	v_pk_add_f32 v[20:21], v[20:21], v[100:101]
	v_pk_add_f32 v[22:23], v[22:23], v[102:103]
	v_mul_f32_e32 v20, 0xbfb8aa3b, v20
	v_mul_f32_e32 v21, 0xbfb8aa3b, v21
	v_mul_f32_e32 v22, 0xbfb8aa3b, v22
	v_mul_f32_e32 v23, 0xbfb8aa3b, v23
	v_exp_f32_e32 v20, v20
	v_exp_f32_e32 v21, v21
	v_exp_f32_e32 v22, v22
	v_exp_f32_e32 v23, v23
	v_add_f32_e32 v20, 1.0, v20
	v_add_f32_e32 v21, 1.0, v21
	v_add_f32_e32 v22, 1.0, v22
	v_add_f32_e32 v23, 1.0, v23
	v_rcp_f32_e32 v20, v20
	v_rcp_f32_e32 v21, v21
	v_rcp_f32_e32 v22, v22
	v_rcp_f32_e32 v23, v23
	v_lshlrev_b32_e32 v153, 16, v108
	v_and_b32_e32 v108, 0xffff0000, v108
	v_lshlrev_b32_e32 v155, 16, v109
	v_and_b32_e32 v109, 0xffff0000, v109
	v_mul_f32_e32 v20, v20, v153
	v_mul_f32_e32 v21, v21, v108
	v_mul_f32_e32 v22, v22, v155
	v_mul_f32_e32 v23, v23, v109
	v_cvt_pk_bf16_f32 v20, v20, v21
	v_cvt_pk_bf16_f32 v21, v22, v23
	v_or_b32_e32 v152, 32, v154
	v_lshlrev_b32_e32 v220, 11, v152
	v_lshl_add_u64 v[150:151], v[142:143], 0, v[220:221]
	global_store_dwordx2 v[150:151], v[20:21], off offset:776
	v_pk_add_f32 v[16:17], v[16:17], v[100:101]
	v_pk_add_f32 v[18:19], v[18:19], v[102:103]
	v_mul_f32_e32 v16, 0xbfb8aa3b, v16
	v_mul_f32_e32 v17, 0xbfb8aa3b, v17
	v_mul_f32_e32 v18, 0xbfb8aa3b, v18
	v_mul_f32_e32 v19, 0xbfb8aa3b, v19
	v_exp_f32_e32 v16, v16
	v_exp_f32_e32 v17, v17
	v_exp_f32_e32 v18, v18
	v_exp_f32_e32 v19, v19
	v_add_f32_e32 v16, 1.0, v16
	v_add_f32_e32 v17, 1.0, v17
	v_add_f32_e32 v18, 1.0, v18
	v_add_f32_e32 v19, 1.0, v19
	v_rcp_f32_e32 v16, v16
	v_rcp_f32_e32 v17, v17
	v_rcp_f32_e32 v18, v18
	v_rcp_f32_e32 v19, v19
	v_lshlrev_b32_e32 v153, 16, v110
	v_and_b32_e32 v110, 0xffff0000, v110
	v_lshlrev_b32_e32 v155, 16, v111
	v_and_b32_e32 v111, 0xffff0000, v111
	v_mul_f32_e32 v16, v16, v153
	v_mul_f32_e32 v17, v17, v110
	v_mul_f32_e32 v18, v18, v155
	v_mul_f32_e32 v19, v19, v111
	v_cvt_pk_bf16_f32 v16, v16, v17
	v_cvt_pk_bf16_f32 v17, v18, v19
	v_or_b32_e32 v152, 48, v154
	v_lshlrev_b32_e32 v220, 11, v152
	v_lshl_add_u64 v[150:151], v[142:143], 0, v[220:221]
	global_store_dwordx2 v[150:151], v[16:17], off offset:776
; __device__ __forceinline__ unsigned cvt_pk_bf16(float lo, float hi) { unsigned r; asm volatile("v_cvt_pk_bf16_f32 %0, %1, %2" : "=v"(r) : "v"(lo), "v"(hi)); return r; }
; __device__ __forceinline__ float sigm(float v) { return __builtin_amdgcn_rcpf(1.0f + __builtin_amdgcn_exp2f(-1.4426950408889634f * v)); }
; #define PG8_BAR __builtin_amdgcn_s_barrier()
;     __device__ __forceinline__ void operator()(const f32x4 (&acc)[2][2][4][2], const Unit& u, int wr, int wc, int fr, int fq) const {
;     ...
;                 const f32x4 bv = *(const f32x4*)(bias + c);
; #pragma unroll
;                 for (int ai = 0; ai < 2; ++ai)
; #pragma unroll
;                     for (int m = 0; m < 4; ++m) {
;                         const size_t row = (size_t)(row0 + ai * HALF + m * 16);
;                         const f32x4 v = acc[ai][bj][m][n] + bv;
;                         const u32x2 yv = *(const u32x2*)(YGS + row * 256 + c);
;                         const float y0 = __uint_as_float(yv.x << 16), y1 = __uint_as_float(yv.x & 0xffff0000u), y2 = __uint_as_float(yv.y << 16), y3 = __uint_as_float(yv.y & 0xffff0000u);
;                         u32x2 w; w.x = cvt_pk_bf16(y0 * sigm(v[0]), y1 * sigm(v[1])); w.y = cvt_pk_bf16(y2 * sigm(v[2]), y3 * sigm(v[3]));
;                         *(u32x2*)(MIX + row * 1024 + 256 + c) = w;
;                         if (m & 1) asm volatile("" ::: "memory");
;                     }
;             }
;     }
; template <class Epi, class Sched, bool ALIGN_EPI = false, bool SP2 = false>
; __device__ __forceinline__ void gemm_phase(PG8_LAS unsigned char* lds, const Gemm g, const Sched& S, const Epi& E) {
;     ...
;         if constexpr (ALIGN_EPI) { if (wr == 0) PG8_BAR; }
;         if constexpr (!Epi::AFTER_DRAIN) { E(acc, cur, wr, wc, fr, fq); S.done(cur); }
;         if (!has_next) break;
; #pragma unroll
;         for (int a = 0; a < 2; ++a)
; #pragma unroll
;             for (int b = 0; b < 2; ++b)
; #pragma unroll
;                 for (int m = 0; m < 4; ++m)
; #pragma unroll
;                     for (int n = 0; n < 2; ++n) acc[a][b][m][n] = (f32x4){0.f, 0.f, 0.f, 0.f};
;         cur = nxt; cA = nA; cB = nB; ++ui;
;         if constexpr (ALIGN_EPI) { if (wr == 1) PG8_BAR; }
	v_pk_add_f32 v[12:13], v[12:13], v[100:101]
	v_pk_add_f32 v[14:15], v[14:15], v[102:103]
	v_mul_f32_e32 v12, 0xbfb8aa3b, v12
	v_mul_f32_e32 v13, 0xbfb8aa3b, v13
	v_mul_f32_e32 v14, 0xbfb8aa3b, v14
	v_mul_f32_e32 v15, 0xbfb8aa3b, v15
	v_exp_f32_e32 v12, v12
	v_exp_f32_e32 v13, v13
	v_exp_f32_e32 v14, v14
	v_exp_f32_e32 v15, v15
	v_add_f32_e32 v12, 1.0, v12
	v_add_f32_e32 v13, 1.0, v13
	v_add_f32_e32 v14, 1.0, v14
	v_add_f32_e32 v15, 1.0, v15
	v_rcp_f32_e32 v12, v12
	v_rcp_f32_e32 v13, v13
	v_rcp_f32_e32 v14, v14
	v_rcp_f32_e32 v15, v15
	v_lshlrev_b32_e32 v153, 16, v112
	v_and_b32_e32 v112, 0xffff0000, v112
	v_lshlrev_b32_e32 v155, 16, v113
	v_and_b32_e32 v113, 0xffff0000, v113
	v_mul_f32_e32 v12, v12, v153
	v_mul_f32_e32 v13, v13, v112
	v_mul_f32_e32 v14, v14, v155
	v_mul_f32_e32 v15, v15, v113
	v_cvt_pk_bf16_f32 v12, v12, v13
	v_cvt_pk_bf16_f32 v13, v14, v15
	v_or_b32_e32 v152, 0x80, v154
	v_lshlrev_b32_e32 v220, 11, v152
	v_lshl_add_u64 v[150:151], v[142:143], 0, v[220:221]
	global_store_dwordx2 v[150:151], v[12:13], off offset:776
	v_pk_add_f32 v[8:9], v[8:9], v[100:101]
	v_pk_add_f32 v[10:11], v[10:11], v[102:103]
	v_mul_f32_e32 v8, 0xbfb8aa3b, v8
	v_mul_f32_e32 v9, 0xbfb8aa3b, v9
	v_mul_f32_e32 v10, 0xbfb8aa3b, v10
	v_mul_f32_e32 v11, 0xbfb8aa3b, v11
	v_exp_f32_e32 v8, v8
	v_exp_f32_e32 v9, v9
	v_exp_f32_e32 v10, v10
	v_exp_f32_e32 v11, v11
	v_add_f32_e32 v8, 1.0, v8
	v_add_f32_e32 v9, 1.0, v9
	v_add_f32_e32 v10, 1.0, v10
	v_add_f32_e32 v11, 1.0, v11
	v_rcp_f32_e32 v8, v8
	v_rcp_f32_e32 v9, v9
	v_rcp_f32_e32 v10, v10
	v_rcp_f32_e32 v11, v11
	v_lshlrev_b32_e32 v153, 16, v114
	v_and_b32_e32 v114, 0xffff0000, v114
	v_lshlrev_b32_e32 v155, 16, v115
	v_and_b32_e32 v115, 0xffff0000, v115
	v_mul_f32_e32 v8, v8, v153
	v_mul_f32_e32 v9, v9, v114
	v_mul_f32_e32 v10, v10, v155
	v_mul_f32_e32 v11, v11, v115
	v_cvt_pk_bf16_f32 v8, v8, v9
	v_cvt_pk_bf16_f32 v9, v10, v11
	v_or_b32_e32 v152, 0x90, v154
	v_lshlrev_b32_e32 v220, 11, v152
	v_lshl_add_u64 v[150:151], v[142:143], 0, v[220:221]
	global_store_dwordx2 v[150:151], v[8:9], off offset:776
	v_pk_add_f32 v[4:5], v[4:5], v[100:101]
	v_pk_add_f32 v[6:7], v[6:7], v[102:103]
	v_mul_f32_e32 v4, 0xbfb8aa3b, v4
	v_mul_f32_e32 v5, 0xbfb8aa3b, v5
	v_mul_f32_e32 v6, 0xbfb8aa3b, v6
	v_mul_f32_e32 v7, 0xbfb8aa3b, v7
	v_exp_f32_e32 v4, v4
	v_exp_f32_e32 v5, v5
	v_exp_f32_e32 v6, v6
	v_exp_f32_e32 v7, v7
	v_add_f32_e32 v4, 1.0, v4
	v_add_f32_e32 v5, 1.0, v5
	v_add_f32_e32 v6, 1.0, v6
	v_add_f32_e32 v7, 1.0, v7
	v_rcp_f32_e32 v4, v4
	v_rcp_f32_e32 v5, v5
	v_rcp_f32_e32 v6, v6
	v_rcp_f32_e32 v7, v7
	v_lshlrev_b32_e32 v153, 16, v116
	v_and_b32_e32 v116, 0xffff0000, v116
	v_lshlrev_b32_e32 v155, 16, v117
	v_and_b32_e32 v117, 0xffff0000, v117
	v_mul_f32_e32 v4, v4, v153
	v_mul_f32_e32 v5, v5, v116
	v_mul_f32_e32 v6, v6, v155
	v_mul_f32_e32 v7, v7, v117
	v_cvt_pk_bf16_f32 v4, v4, v5
	v_cvt_pk_bf16_f32 v5, v6, v7
	v_or_b32_e32 v152, 0xa0, v154
	v_lshlrev_b32_e32 v220, 11, v152
	v_lshl_add_u64 v[150:151], v[142:143], 0, v[220:221]
	global_store_dwordx2 v[150:151], v[4:5], off offset:776
	v_pk_add_f32 v[0:1], v[0:1], v[100:101]
	v_pk_add_f32 v[2:3], v[2:3], v[102:103]
	v_mul_f32_e32 v0, 0xbfb8aa3b, v0
	v_mul_f32_e32 v1, 0xbfb8aa3b, v1
	v_mul_f32_e32 v2, 0xbfb8aa3b, v2
	v_mul_f32_e32 v3, 0xbfb8aa3b, v3
	v_exp_f32_e32 v0, v0
	v_exp_f32_e32 v1, v1
	v_exp_f32_e32 v2, v2
	v_exp_f32_e32 v3, v3
	v_add_f32_e32 v0, 1.0, v0
	v_add_f32_e32 v1, 1.0, v1
	v_add_f32_e32 v2, 1.0, v2
	v_add_f32_e32 v3, 1.0, v3
	v_rcp_f32_e32 v0, v0
	v_rcp_f32_e32 v1, v1
	v_rcp_f32_e32 v2, v2
	v_rcp_f32_e32 v3, v3
	v_lshlrev_b32_e32 v153, 16, v118
	v_and_b32_e32 v118, 0xffff0000, v118
	v_lshlrev_b32_e32 v155, 16, v119
	v_and_b32_e32 v119, 0xffff0000, v119
	v_mul_f32_e32 v0, v0, v153
	v_mul_f32_e32 v1, v1, v118
	v_mul_f32_e32 v2, v2, v155
	v_mul_f32_e32 v3, v3, v119
	v_cvt_pk_bf16_f32 v0, v0, v1
	v_cvt_pk_bf16_f32 v1, v2, v3
	v_or_b32_e32 v152, 0xb0, v154
	v_lshlrev_b32_e32 v220, 11, v152
	v_lshl_add_u64 v[150:151], v[142:143], 0, v[220:221]
	global_store_dwordx2 v[150:151], v[0:1], off offset:776
	s_cbranch_vccnz .LBB0_827
	s_andn2_b64 vcc, exec, s[24:25]
	s_cbranch_vccnz .LBB0_826
	s_barrier
	s_branch .LBB0_826

; __device__ __forceinline__ unsigned cvt_pk_bf16(float lo, float hi) { unsigned r; asm volatile("v_cvt_pk_bf16_f32 %0, %1, %2" : "=v"(r) : "v"(lo), "v"(hi)); return r; }
;     __device__ __forceinline__ void operator()(const f32x4 (&acc)[2][2][4][2], const Unit& u, int wr, int wc, int fr, int fq) const {
;         typedef unsigned u32x2 __attribute__((ext_vector_type(2)));
;         const int col0 = u.pn * BM + wc * 32 + 4 * fq;
; #pragma unroll
;         for (int ai = 0; ai < 2; ++ai)
; #pragma unroll
;             for (int m = 0; m < 4; ++m) {
;                 const int row = u.pm * BM + ai * HALF + wr * 64 + m * 16 + fr;
;                 const size_t off = (size_t)row * 1024 + col0;
;                 float ss = 0.f;
; #pragma unroll
;                 for (int bj = 0; bj < 2; ++bj)
; #pragma unroll
;                     for (int n = 0; n < 2; ++n) {
;                         f32x4 bs;
;                         { const u32x2 hb = *(const u32x2*)(baseh + off + bj * HALF + n * 16); bs = (f32x4){__uint_as_float(hb.x << 16), __uint_as_float(hb.x & 0xffff0000u), __uint_as_float(hb.y << 16), __uint_as_float(hb.y & 0xffff0000u)}; }
;                         const f32x4 o = bs + acc[ai][bj][m][n];
;                         if (NEXT) { ss += (o[0] * o[0] + o[1] * o[1]) + (o[2] * o[2] + o[3] * o[3]);
;                             u32x2 w; w.x = cvt_pk_bf16(o[0], o[1]); w.y = cvt_pk_bf16(o[2], o[3]); *(u32x2*)(XN + off + bj * HALF + n * 16) = w; }
;                         else *(f32x4*)(out + off + bj * HALF + n * 16) = o;
;                     }
;                 if (NEXT) { ss += __shfl_xor(ss, 16); ss += __shfl_xor(ss, 32); if (fq == 0) atomicAdd(rowss + row, ss); }
.LBB0_919:
	v_lshl_add_u32 v136, s74, 8, v138
	v_lshl_or_b32 v134, s62, 8, v140
	v_lshlrev_b32_e32 v196, 11, v136
	v_lshl_add_u32 v196, v134, 1, v196
	v_readlane_b32 s14, v253, 46
	v_readlane_b32 s15, v253, 47
	v_readlane_b32 s90, v254, 49
	v_readlane_b32 s91, v254, 50
	v_readlane_b32 s89, v254, 58
	v_readlane_b32 s88, v254, 60
	global_load_dwordx2 v[148:149], v196, s[94:95]
	global_load_dwordx2 v[150:151], v196, s[94:95] offset:32
	global_load_dwordx2 v[152:153], v196, s[94:95] offset:256
	global_load_dwordx2 v[154:155], v196, s[94:95] offset:288
	v_add_u32_e32 v197, 0x8000, v196
	global_load_dwordx2 v[156:157], v197, s[94:95]
	global_load_dwordx2 v[158:159], v197, s[94:95] offset:32
	global_load_dwordx2 v[160:161], v197, s[94:95] offset:256
	global_load_dwordx2 v[162:163], v197, s[94:95] offset:288
	v_add_u32_e32 v197, 0x10000, v196
	global_load_dwordx2 v[164:165], v197, s[94:95]
	global_load_dwordx2 v[166:167], v197, s[94:95] offset:32
	global_load_dwordx2 v[168:169], v197, s[94:95] offset:256
	global_load_dwordx2 v[170:171], v197, s[94:95] offset:288
	v_add_u32_e32 v197, 0x18000, v196
	global_load_dwordx2 v[172:173], v197, s[94:95]
	global_load_dwordx2 v[174:175], v197, s[94:95] offset:32
	global_load_dwordx2 v[176:177], v197, s[94:95] offset:256
	global_load_dwordx2 v[178:179], v197, s[94:95] offset:288
	v_add_u32_e32 v197, 0x40000, v196
	global_load_dwordx2 v[180:181], v197, s[94:95]
	global_load_dwordx2 v[182:183], v197, s[94:95] offset:32
	global_load_dwordx2 v[184:185], v197, s[94:95] offset:256
	global_load_dwordx2 v[186:187], v197, s[94:95] offset:288
	v_add_u32_e32 v197, 0x48000, v196
	global_load_dwordx2 v[188:189], v197, s[94:95]
	global_load_dwordx2 v[190:191], v197, s[94:95] offset:32
	global_load_dwordx2 v[192:193], v197, s[94:95] offset:256
	global_load_dwordx2 v[194:195], v197, s[94:95] offset:288
	v_and_b32_e32 v201, 64, v237
	v_xor_b32_e32 v200, 16, v237
	v_add_u32_e32 v201, 64, v201
	v_cmp_lt_i32_e32 vcc, v200, v201
	s_nop 1
	v_cndmask_b32_e32 v200, v237, v200, vcc
	v_lshlrev_b32_e32 v146, 2, v200
	v_xor_b32_e32 v200, 32, v237
	v_cmp_lt_i32_e32 vcc, v200, v201
	s_nop 1
	v_cndmask_b32_e32 v200, v237, v200, vcc
	v_lshlrev_b32_e32 v147, 2, v200
	s_waitcnt vmcnt(20)
	v_lshlrev_b32_e32 v200, 16, v148
	v_and_b32_e32 v201, 0xffff0000, v148
	v_lshlrev_b32_e32 v148, 16, v149
	v_and_b32_e32 v149, 0xffff0000, v149
	v_pk_add_f32 v[124:125], v[124:125], v[200:201]
	v_pk_add_f32 v[126:127], v[126:127], v[148:149]
	v_mul_f32_e32 v198, v124, v124
	v_fmac_f32_e32 v198, v125, v125
	v_fmac_f32_e32 v198, v126, v126
	v_fmac_f32_e32 v198, v127, v127
	v_cvt_pk_bf16_f32 v124, v124, v125
	v_cvt_pk_bf16_f32 v125, v126, v127
	v_lshlrev_b32_e32 v200, 16, v150
	v_and_b32_e32 v201, 0xffff0000, v150
	v_lshlrev_b32_e32 v150, 16, v151
	v_and_b32_e32 v151, 0xffff0000, v151
	v_pk_add_f32 v[120:121], v[120:121], v[200:201]
	v_pk_add_f32 v[122:123], v[122:123], v[150:151]
	v_fmac_f32_e32 v198, v120, v120
	v_fmac_f32_e32 v198, v121, v121
	v_fmac_f32_e32 v198, v122, v122
	v_fmac_f32_e32 v198, v123, v123
	v_cvt_pk_bf16_f32 v120, v120, v121
	v_cvt_pk_bf16_f32 v121, v122, v123
	v_lshlrev_b32_e32 v200, 16, v152
	v_and_b32_e32 v201, 0xffff0000, v152
	v_lshlrev_b32_e32 v152, 16, v153
	v_and_b32_e32 v153, 0xffff0000, v153
	v_pk_add_f32 v[116:117], v[116:117], v[200:201]
	v_pk_add_f32 v[118:119], v[118:119], v[152:153]
	v_fmac_f32_e32 v198, v116, v116
	v_fmac_f32_e32 v198, v117, v117
	v_fmac_f32_e32 v198, v118, v118
	v_fmac_f32_e32 v198, v119, v119
	v_cvt_pk_bf16_f32 v116, v116, v117
	v_cvt_pk_bf16_f32 v117, v118, v119
	v_lshlrev_b32_e32 v200, 16, v154
	v_and_b32_e32 v201, 0xffff0000, v154
	v_lshlrev_b32_e32 v154, 16, v155
	v_and_b32_e32 v155, 0xffff0000, v155
	v_pk_add_f32 v[112:113], v[112:113], v[200:201]
	v_pk_add_f32 v[114:115], v[114:115], v[154:155]
	v_fmac_f32_e32 v198, v112, v112
	v_fmac_f32_e32 v198, v113, v113
	v_fmac_f32_e32 v198, v114, v114
	v_fmac_f32_e32 v198, v115, v115
	v_cvt_pk_bf16_f32 v112, v112, v113
	v_cvt_pk_bf16_f32 v113, v114, v115
	global_store_dwordx2 v196, v[124:125], s[94:95]
	global_store_dwordx2 v196, v[120:121], s[94:95] offset:32
	global_store_dwordx2 v196, v[116:117], s[94:95] offset:256
	global_store_dwordx2 v196, v[112:113], s[94:95] offset:288
	ds_bpermute_b32 v199, v146, v198
	s_waitcnt lgkmcnt(0)
	v_add_f32_e32 v198, v198, v199
	ds_bpermute_b32 v199, v147, v198
	v_lshlrev_b32_e32 v197, 2, v136
	s_waitcnt lgkmcnt(0)
	v_add_f32_e32 v198, v198, v199
	s_and_saveexec_b64 s[2:3], s[0:1]
	s_cbranch_execz .Lmy_er_skip0
	global_atomic_add_f32 v197, v198, s[14:15]
; __device__ __forceinline__ unsigned cvt_pk_bf16(float lo, float hi) { unsigned r; asm volatile("v_cvt_pk_bf16_f32 %0, %1, %2" : "=v"(r) : "v"(lo), "v"(hi)); return r; }
;     __device__ __forceinline__ void operator()(const f32x4 (&acc)[2][2][4][2], const Unit& u, int wr, int wc, int fr, int fq) const {
;     ...
;         for (int ai = 0; ai < 2; ++ai)
; #pragma unroll
;             for (int m = 0; m < 4; ++m) {
;                 const int row = u.pm * BM + ai * HALF + wr * 64 + m * 16 + fr;
;                 const size_t off = (size_t)row * 1024 + col0;
;                 float ss = 0.f;
; #pragma unroll
;                 for (int bj = 0; bj < 2; ++bj)
; #pragma unroll
;                     for (int n = 0; n < 2; ++n) {
;                         f32x4 bs;
;                         { const u32x2 hb = *(const u32x2*)(baseh + off + bj * HALF + n * 16); bs = (f32x4){__uint_as_float(hb.x << 16), __uint_as_float(hb.x & 0xffff0000u), __uint_as_float(hb.y << 16), __uint_as_float(hb.y & 0xffff0000u)}; }
;                         const f32x4 o = bs + acc[ai][bj][m][n];
;                         if (NEXT) { ss += (o[0] * o[0] + o[1] * o[1]) + (o[2] * o[2] + o[3] * o[3]);
;                             u32x2 w; w.x = cvt_pk_bf16(o[0], o[1]); w.y = cvt_pk_bf16(o[2], o[3]); *(u32x2*)(XN + off + bj * HALF + n * 16) = w; }
;                         else *(f32x4*)(out + off + bj * HALF + n * 16) = o;
;                     }
;                 if (NEXT) { ss += __shfl_xor(ss, 16); ss += __shfl_xor(ss, 32); if (fq == 0) atomicAdd(rowss + row, ss); }
;                 if (m & 1) asm volatile("" ::: "memory");
;             }
.Lmy_er_skip0:
	s_or_b64 exec, exec, s[2:3]
	s_waitcnt vmcnt(21)
	v_lshlrev_b32_e32 v200, 16, v156
	v_and_b32_e32 v201, 0xffff0000, v156
	v_lshlrev_b32_e32 v156, 16, v157
	v_and_b32_e32 v157, 0xffff0000, v157
	v_pk_add_f32 v[108:109], v[108:109], v[200:201]
	v_pk_add_f32 v[110:111], v[110:111], v[156:157]
	v_mul_f32_e32 v198, v108, v108
	v_fmac_f32_e32 v198, v109, v109
	v_fmac_f32_e32 v198, v110, v110
	v_fmac_f32_e32 v198, v111, v111
	v_cvt_pk_bf16_f32 v108, v108, v109
	v_cvt_pk_bf16_f32 v109, v110, v111
	v_lshlrev_b32_e32 v200, 16, v158
	v_and_b32_e32 v201, 0xffff0000, v158
	v_lshlrev_b32_e32 v158, 16, v159
	v_and_b32_e32 v159, 0xffff0000, v159
	v_pk_add_f32 v[104:105], v[104:105], v[200:201]
	v_pk_add_f32 v[106:107], v[106:107], v[158:159]
	v_fmac_f32_e32 v198, v104, v104
	v_fmac_f32_e32 v198, v105, v105
	v_fmac_f32_e32 v198, v106, v106
	v_fmac_f32_e32 v198, v107, v107
	v_cvt_pk_bf16_f32 v104, v104, v105
	v_cvt_pk_bf16_f32 v105, v106, v107
	v_lshlrev_b32_e32 v200, 16, v160
	v_and_b32_e32 v201, 0xffff0000, v160
	v_lshlrev_b32_e32 v160, 16, v161
	v_and_b32_e32 v161, 0xffff0000, v161
	v_pk_add_f32 v[100:101], v[100:101], v[200:201]
	v_pk_add_f32 v[102:103], v[102:103], v[160:161]
	v_fmac_f32_e32 v198, v100, v100
	v_fmac_f32_e32 v198, v101, v101
	v_fmac_f32_e32 v198, v102, v102
	v_fmac_f32_e32 v198, v103, v103
	v_cvt_pk_bf16_f32 v100, v100, v101
	v_cvt_pk_bf16_f32 v101, v102, v103
	v_lshlrev_b32_e32 v200, 16, v162
	v_and_b32_e32 v201, 0xffff0000, v162
	v_lshlrev_b32_e32 v162, 16, v163
	v_and_b32_e32 v163, 0xffff0000, v163
	v_pk_add_f32 v[96:97], v[96:97], v[200:201]
	v_pk_add_f32 v[98:99], v[98:99], v[162:163]
	v_fmac_f32_e32 v198, v96, v96
	v_fmac_f32_e32 v198, v97, v97
	v_fmac_f32_e32 v198, v98, v98
	v_fmac_f32_e32 v198, v99, v99
	v_cvt_pk_bf16_f32 v96, v96, v97
	v_cvt_pk_bf16_f32 v97, v98, v99
	v_add_u32_e32 v197, 0x8000, v196
	global_store_dwordx2 v197, v[108:109], s[94:95]
	global_store_dwordx2 v197, v[104:105], s[94:95] offset:32
	global_store_dwordx2 v197, v[100:101], s[94:95] offset:256
	global_store_dwordx2 v197, v[96:97], s[94:95] offset:288
	ds_bpermute_b32 v199, v146, v198
	s_waitcnt lgkmcnt(0)
	v_add_f32_e32 v198, v198, v199
	ds_bpermute_b32 v199, v147, v198
	v_or_b32_e32 v197, 16, v136
	v_lshlrev_b32_e32 v197, 2, v197
	s_waitcnt lgkmcnt(0)
	v_add_f32_e32 v198, v198, v199
	s_and_saveexec_b64 s[2:3], s[0:1]
	s_cbranch_execz .Lmy_er_skip1
	global_atomic_add_f32 v197, v198, s[14:15]
.Lmy_er_skip1:
	s_or_b64 exec, exec, s[2:3]
	v_add_u32_e32 v197, 0x50000, v196
	global_load_dwordx2 v[112:113], v197, s[94:95]
	global_load_dwordx2 v[114:115], v197, s[94:95] offset:32
	global_load_dwordx2 v[116:117], v197, s[94:95] offset:256
	global_load_dwordx2 v[118:119], v197, s[94:95] offset:288
	v_add_u32_e32 v197, 0x58000, v196
	global_load_dwordx2 v[120:121], v197, s[94:95]
	global_load_dwordx2 v[122:123], v197, s[94:95] offset:32
	global_load_dwordx2 v[124:125], v197, s[94:95] offset:256
	global_load_dwordx2 v[126:127], v197, s[94:95] offset:288
	s_waitcnt vmcnt(30)
	v_lshlrev_b32_e32 v200, 16, v164
	v_and_b32_e32 v201, 0xffff0000, v164
	v_lshlrev_b32_e32 v164, 16, v165
	v_and_b32_e32 v165, 0xffff0000, v165
	v_pk_add_f32 v[92:93], v[92:93], v[200:201]
	v_pk_add_f32 v[94:95], v[94:95], v[164:165]
	v_mul_f32_e32 v198, v92, v92
	v_fmac_f32_e32 v198, v93, v93
	v_fmac_f32_e32 v198, v94, v94
	v_fmac_f32_e32 v198, v95, v95
	v_cvt_pk_bf16_f32 v92, v92, v93
	v_cvt_pk_bf16_f32 v93, v94, v95
	v_lshlrev_b32_e32 v200, 16, v166
	v_and_b32_e32 v201, 0xffff0000, v166
	v_lshlrev_b32_e32 v166, 16, v167
	v_and_b32_e32 v167, 0xffff0000, v167
	v_pk_add_f32 v[88:89], v[88:89], v[200:201]
	v_pk_add_f32 v[90:91], v[90:91], v[166:167]
	v_fmac_f32_e32 v198, v88, v88
	v_fmac_f32_e32 v198, v89, v89
	v_fmac_f32_e32 v198, v90, v90
	v_fmac_f32_e32 v198, v91, v91
	v_cvt_pk_bf16_f32 v88, v88, v89
	v_cvt_pk_bf16_f32 v89, v90, v91
	v_lshlrev_b32_e32 v200, 16, v168
	v_and_b32_e32 v201, 0xffff0000, v168
	v_lshlrev_b32_e32 v168, 16, v169
	v_and_b32_e32 v169, 0xffff0000, v169
	v_pk_add_f32 v[84:85], v[84:85], v[200:201]
	v_pk_add_f32 v[86:87], v[86:87], v[168:169]
	v_fmac_f32_e32 v198, v84, v84
	v_fmac_f32_e32 v198, v85, v85
	v_fmac_f32_e32 v198, v86, v86
	v_fmac_f32_e32 v198, v87, v87
	v_cvt_pk_bf16_f32 v84, v84, v85
	v_cvt_pk_bf16_f32 v85, v86, v87
	v_lshlrev_b32_e32 v200, 16, v170
	v_and_b32_e32 v201, 0xffff0000, v170
	v_lshlrev_b32_e32 v170, 16, v171
	v_and_b32_e32 v171, 0xffff0000, v171
	v_pk_add_f32 v[80:81], v[80:81], v[200:201]
	v_pk_add_f32 v[82:83], v[82:83], v[170:171]
	v_fmac_f32_e32 v198, v80, v80
	v_fmac_f32_e32 v198, v81, v81
	v_fmac_f32_e32 v198, v82, v82
	v_fmac_f32_e32 v198, v83, v83
	v_cvt_pk_bf16_f32 v80, v80, v81
	v_cvt_pk_bf16_f32 v81, v82, v83
	v_add_u32_e32 v197, 0x10000, v196
	global_store_dwordx2 v197, v[92:93], s[94:95]
	global_store_dwordx2 v197, v[88:89], s[94:95] offset:32
	global_store_dwordx2 v197, v[84:85], s[94:95] offset:256
	global_store_dwordx2 v197, v[80:81], s[94:95] offset:288
	ds_bpermute_b32 v199, v146, v198
	s_waitcnt lgkmcnt(0)
	v_add_f32_e32 v198, v198, v199
	ds_bpermute_b32 v199, v147, v198
	v_or_b32_e32 v197, 32, v136
	v_lshlrev_b32_e32 v197, 2, v197
	s_waitcnt lgkmcnt(0)
	v_add_f32_e32 v198, v198, v199
	s_and_saveexec_b64 s[2:3], s[0:1]
	s_cbranch_execz .Lmy_er_skip2
	global_atomic_add_f32 v197, v198, s[14:15]
; __device__ __forceinline__ unsigned cvt_pk_bf16(float lo, float hi) { unsigned r; asm volatile("v_cvt_pk_bf16_f32 %0, %1, %2" : "=v"(r) : "v"(lo), "v"(hi)); return r; }
;     __device__ __forceinline__ void operator()(const f32x4 (&acc)[2][2][4][2], const Unit& u, int wr, int wc, int fr, int fq) const {
;     ...
;         for (int ai = 0; ai < 2; ++ai)
; #pragma unroll
;             for (int m = 0; m < 4; ++m) {
;                 const int row = u.pm * BM + ai * HALF + wr * 64 + m * 16 + fr;
;                 const size_t off = (size_t)row * 1024 + col0;
;                 float ss = 0.f;
; #pragma unroll
;                 for (int bj = 0; bj < 2; ++bj)
; #pragma unroll
;                     for (int n = 0; n < 2; ++n) {
;                         f32x4 bs;
;                         { const u32x2 hb = *(const u32x2*)(baseh + off + bj * HALF + n * 16); bs = (f32x4){__uint_as_float(hb.x << 16), __uint_as_float(hb.x & 0xffff0000u), __uint_as_float(hb.y << 16), __uint_as_float(hb.y & 0xffff0000u)}; }
;                         const f32x4 o = bs + acc[ai][bj][m][n];
;                         if (NEXT) { ss += (o[0] * o[0] + o[1] * o[1]) + (o[2] * o[2] + o[3] * o[3]);
;                             u32x2 w; w.x = cvt_pk_bf16(o[0], o[1]); w.y = cvt_pk_bf16(o[2], o[3]); *(u32x2*)(XN + off + bj * HALF + n * 16) = w; }
;                         else *(f32x4*)(out + off + bj * HALF + n * 16) = o;
;                     }
;                 if (NEXT) { ss += __shfl_xor(ss, 16); ss += __shfl_xor(ss, 32); if (fq == 0) atomicAdd(rowss + row, ss); }
;                 if (m & 1) asm volatile("" ::: "memory");
;             }
.Lmy_er_skip2:
	s_or_b64 exec, exec, s[2:3]
	s_waitcnt vmcnt(31)
	v_lshlrev_b32_e32 v200, 16, v172
	v_and_b32_e32 v201, 0xffff0000, v172
	v_lshlrev_b32_e32 v172, 16, v173
	v_and_b32_e32 v173, 0xffff0000, v173
	v_pk_add_f32 v[76:77], v[76:77], v[200:201]
	v_pk_add_f32 v[78:79], v[78:79], v[172:173]
	v_mul_f32_e32 v198, v76, v76
	v_fmac_f32_e32 v198, v77, v77
	v_fmac_f32_e32 v198, v78, v78
	v_fmac_f32_e32 v198, v79, v79
	v_cvt_pk_bf16_f32 v76, v76, v77
	v_cvt_pk_bf16_f32 v77, v78, v79
	v_lshlrev_b32_e32 v200, 16, v174
	v_and_b32_e32 v201, 0xffff0000, v174
	v_lshlrev_b32_e32 v174, 16, v175
	v_and_b32_e32 v175, 0xffff0000, v175
	v_pk_add_f32 v[72:73], v[72:73], v[200:201]
	v_pk_add_f32 v[74:75], v[74:75], v[174:175]
	v_fmac_f32_e32 v198, v72, v72
	v_fmac_f32_e32 v198, v73, v73
	v_fmac_f32_e32 v198, v74, v74
	v_fmac_f32_e32 v198, v75, v75
	v_cvt_pk_bf16_f32 v72, v72, v73
	v_cvt_pk_bf16_f32 v73, v74, v75
	v_lshlrev_b32_e32 v200, 16, v176
	v_and_b32_e32 v201, 0xffff0000, v176
	v_lshlrev_b32_e32 v176, 16, v177
	v_and_b32_e32 v177, 0xffff0000, v177
	v_pk_add_f32 v[68:69], v[68:69], v[200:201]
	v_pk_add_f32 v[70:71], v[70:71], v[176:177]
	v_fmac_f32_e32 v198, v68, v68
	v_fmac_f32_e32 v198, v69, v69
	v_fmac_f32_e32 v198, v70, v70
	v_fmac_f32_e32 v198, v71, v71
	v_cvt_pk_bf16_f32 v68, v68, v69
	v_cvt_pk_bf16_f32 v69, v70, v71
	v_lshlrev_b32_e32 v200, 16, v178
	v_and_b32_e32 v201, 0xffff0000, v178
	v_lshlrev_b32_e32 v178, 16, v179
	v_and_b32_e32 v179, 0xffff0000, v179
	v_pk_add_f32 v[64:65], v[64:65], v[200:201]
	v_pk_add_f32 v[66:67], v[66:67], v[178:179]
	v_fmac_f32_e32 v198, v64, v64
	v_fmac_f32_e32 v198, v65, v65
	v_fmac_f32_e32 v198, v66, v66
	v_fmac_f32_e32 v198, v67, v67
	v_cvt_pk_bf16_f32 v64, v64, v65
	v_cvt_pk_bf16_f32 v65, v66, v67
	v_add_u32_e32 v197, 0x18000, v196
	global_store_dwordx2 v197, v[76:77], s[94:95]
	global_store_dwordx2 v197, v[72:73], s[94:95] offset:32
	global_store_dwordx2 v197, v[68:69], s[94:95] offset:256
	global_store_dwordx2 v197, v[64:65], s[94:95] offset:288
	ds_bpermute_b32 v199, v146, v198
	s_waitcnt lgkmcnt(0)
	v_add_f32_e32 v198, v198, v199
	ds_bpermute_b32 v199, v147, v198
	v_or_b32_e32 v197, 48, v136
	v_lshlrev_b32_e32 v197, 2, v197
	s_waitcnt lgkmcnt(0)
	v_add_f32_e32 v198, v198, v199
	s_and_saveexec_b64 s[2:3], s[0:1]
	s_cbranch_execz .Lmy_er_skip3
	global_atomic_add_f32 v197, v198, s[14:15]
.Lmy_er_skip3:
	s_or_b64 exec, exec, s[2:3]
	s_waitcnt vmcnt(32)
	v_lshlrev_b32_e32 v200, 16, v180
	v_and_b32_e32 v201, 0xffff0000, v180
	v_lshlrev_b32_e32 v180, 16, v181
	v_and_b32_e32 v181, 0xffff0000, v181
	v_pk_add_f32 v[60:61], v[60:61], v[200:201]
	v_pk_add_f32 v[62:63], v[62:63], v[180:181]
	v_mul_f32_e32 v198, v60, v60
	v_fmac_f32_e32 v198, v61, v61
	v_fmac_f32_e32 v198, v62, v62
	v_fmac_f32_e32 v198, v63, v63
	v_cvt_pk_bf16_f32 v60, v60, v61
	v_cvt_pk_bf16_f32 v61, v62, v63
	v_lshlrev_b32_e32 v200, 16, v182
	v_and_b32_e32 v201, 0xffff0000, v182
	v_lshlrev_b32_e32 v182, 16, v183
	v_and_b32_e32 v183, 0xffff0000, v183
	v_pk_add_f32 v[56:57], v[56:57], v[200:201]
	v_pk_add_f32 v[58:59], v[58:59], v[182:183]
	v_fmac_f32_e32 v198, v56, v56
	v_fmac_f32_e32 v198, v57, v57
	v_fmac_f32_e32 v198, v58, v58
	v_fmac_f32_e32 v198, v59, v59
	v_cvt_pk_bf16_f32 v56, v56, v57
	v_cvt_pk_bf16_f32 v57, v58, v59
	v_lshlrev_b32_e32 v200, 16, v184
	v_and_b32_e32 v201, 0xffff0000, v184
	v_lshlrev_b32_e32 v184, 16, v185
	v_and_b32_e32 v185, 0xffff0000, v185
	v_pk_add_f32 v[52:53], v[52:53], v[200:201]
	v_pk_add_f32 v[54:55], v[54:55], v[184:185]
	v_fmac_f32_e32 v198, v52, v52
	v_fmac_f32_e32 v198, v53, v53
	v_fmac_f32_e32 v198, v54, v54
	v_fmac_f32_e32 v198, v55, v55
	v_cvt_pk_bf16_f32 v52, v52, v53
	v_cvt_pk_bf16_f32 v53, v54, v55
	v_lshlrev_b32_e32 v200, 16, v186
	v_and_b32_e32 v201, 0xffff0000, v186
	v_lshlrev_b32_e32 v186, 16, v187
	v_and_b32_e32 v187, 0xffff0000, v187
	v_pk_add_f32 v[48:49], v[48:49], v[200:201]
	v_pk_add_f32 v[50:51], v[50:51], v[186:187]
	v_fmac_f32_e32 v198, v48, v48
	v_fmac_f32_e32 v198, v49, v49
	v_fmac_f32_e32 v198, v50, v50
	v_fmac_f32_e32 v198, v51, v51
	v_cvt_pk_bf16_f32 v48, v48, v49
	v_cvt_pk_bf16_f32 v49, v50, v51
	v_add_u32_e32 v197, 0x40000, v196
	global_store_dwordx2 v197, v[60:61], s[94:95]
	global_store_dwordx2 v197, v[56:57], s[94:95] offset:32
	global_store_dwordx2 v197, v[52:53], s[94:95] offset:256
	global_store_dwordx2 v197, v[48:49], s[94:95] offset:288
	ds_bpermute_b32 v199, v146, v198
	s_waitcnt lgkmcnt(0)
	v_add_f32_e32 v198, v198, v199
	ds_bpermute_b32 v199, v147, v198
	v_or_b32_e32 v197, 0x80, v136
	v_lshlrev_b32_e32 v197, 2, v197
	s_waitcnt lgkmcnt(0)
	v_add_f32_e32 v198, v198, v199
	s_and_saveexec_b64 s[2:3], s[0:1]
	s_cbranch_execz .Lmy_er_skip4
	global_atomic_add_f32 v197, v198, s[14:15]
; __device__ __forceinline__ unsigned cvt_pk_bf16(float lo, float hi) { unsigned r; asm volatile("v_cvt_pk_bf16_f32 %0, %1, %2" : "=v"(r) : "v"(lo), "v"(hi)); return r; }
;     __device__ __forceinline__ void operator()(const f32x4 (&acc)[2][2][4][2], const Unit& u, int wr, int wc, int fr, int fq) const {
;     ...
;         for (int ai = 0; ai < 2; ++ai)
; #pragma unroll
;             for (int m = 0; m < 4; ++m) {
;                 const int row = u.pm * BM + ai * HALF + wr * 64 + m * 16 + fr;
;                 const size_t off = (size_t)row * 1024 + col0;
;                 float ss = 0.f;
; #pragma unroll
;                 for (int bj = 0; bj < 2; ++bj)
; #pragma unroll
;                     for (int n = 0; n < 2; ++n) {
;                         f32x4 bs;
;                         { const u32x2 hb = *(const u32x2*)(baseh + off + bj * HALF + n * 16); bs = (f32x4){__uint_as_float(hb.x << 16), __uint_as_float(hb.x & 0xffff0000u), __uint_as_float(hb.y << 16), __uint_as_float(hb.y & 0xffff0000u)}; }
;                         const f32x4 o = bs + acc[ai][bj][m][n];
;                         if (NEXT) { ss += (o[0] * o[0] + o[1] * o[1]) + (o[2] * o[2] + o[3] * o[3]);
;                             u32x2 w; w.x = cvt_pk_bf16(o[0], o[1]); w.y = cvt_pk_bf16(o[2], o[3]); *(u32x2*)(XN + off + bj * HALF + n * 16) = w; }
;                         else *(f32x4*)(out + off + bj * HALF + n * 16) = o;
;                     }
;                 if (NEXT) { ss += __shfl_xor(ss, 16); ss += __shfl_xor(ss, 32); if (fq == 0) atomicAdd(rowss + row, ss); }
;                 if (m & 1) asm volatile("" ::: "memory");
;             }
.Lmy_er_skip4:
	s_or_b64 exec, exec, s[2:3]
	s_waitcnt vmcnt(33)
	v_lshlrev_b32_e32 v200, 16, v188
	v_and_b32_e32 v201, 0xffff0000, v188
	v_lshlrev_b32_e32 v188, 16, v189
	v_and_b32_e32 v189, 0xffff0000, v189
	v_pk_add_f32 v[44:45], v[44:45], v[200:201]
	v_pk_add_f32 v[46:47], v[46:47], v[188:189]
	v_mul_f32_e32 v198, v44, v44
	v_fmac_f32_e32 v198, v45, v45
	v_fmac_f32_e32 v198, v46, v46
	v_fmac_f32_e32 v198, v47, v47
	v_cvt_pk_bf16_f32 v44, v44, v45
	v_cvt_pk_bf16_f32 v45, v46, v47
	v_lshlrev_b32_e32 v200, 16, v190
	v_and_b32_e32 v201, 0xffff0000, v190
	v_lshlrev_b32_e32 v190, 16, v191
	v_and_b32_e32 v191, 0xffff0000, v191
	v_pk_add_f32 v[40:41], v[40:41], v[200:201]
	v_pk_add_f32 v[42:43], v[42:43], v[190:191]
	v_fmac_f32_e32 v198, v40, v40
	v_fmac_f32_e32 v198, v41, v41
	v_fmac_f32_e32 v198, v42, v42
	v_fmac_f32_e32 v198, v43, v43
	v_cvt_pk_bf16_f32 v40, v40, v41
	v_cvt_pk_bf16_f32 v41, v42, v43
	v_lshlrev_b32_e32 v200, 16, v192
	v_and_b32_e32 v201, 0xffff0000, v192
	v_lshlrev_b32_e32 v192, 16, v193
	v_and_b32_e32 v193, 0xffff0000, v193
	v_pk_add_f32 v[36:37], v[36:37], v[200:201]
	v_pk_add_f32 v[38:39], v[38:39], v[192:193]
	v_fmac_f32_e32 v198, v36, v36
	v_fmac_f32_e32 v198, v37, v37
	v_fmac_f32_e32 v198, v38, v38
	v_fmac_f32_e32 v198, v39, v39
	v_cvt_pk_bf16_f32 v36, v36, v37
	v_cvt_pk_bf16_f32 v37, v38, v39
	v_lshlrev_b32_e32 v200, 16, v194
	v_and_b32_e32 v201, 0xffff0000, v194
	v_lshlrev_b32_e32 v194, 16, v195
	v_and_b32_e32 v195, 0xffff0000, v195
	v_pk_add_f32 v[32:33], v[32:33], v[200:201]
	v_pk_add_f32 v[34:35], v[34:35], v[194:195]
	v_fmac_f32_e32 v198, v32, v32
	v_fmac_f32_e32 v198, v33, v33
	v_fmac_f32_e32 v198, v34, v34
	v_fmac_f32_e32 v198, v35, v35
	v_cvt_pk_bf16_f32 v32, v32, v33
	v_cvt_pk_bf16_f32 v33, v34, v35
	v_add_u32_e32 v197, 0x48000, v196
	global_store_dwordx2 v197, v[44:45], s[94:95]
	global_store_dwordx2 v197, v[40:41], s[94:95] offset:32
	global_store_dwordx2 v197, v[36:37], s[94:95] offset:256
	global_store_dwordx2 v197, v[32:33], s[94:95] offset:288
	ds_bpermute_b32 v199, v146, v198
	s_waitcnt lgkmcnt(0)
	v_add_f32_e32 v198, v198, v199
	ds_bpermute_b32 v199, v147, v198
	v_or_b32_e32 v197, 0x90, v136
	v_lshlrev_b32_e32 v197, 2, v197
	s_waitcnt lgkmcnt(0)
	v_add_f32_e32 v198, v198, v199
	s_and_saveexec_b64 s[2:3], s[0:1]
	s_cbranch_execz .Lmy_er_skip5
	global_atomic_add_f32 v197, v198, s[14:15]
.Lmy_er_skip5:
	s_or_b64 exec, exec, s[2:3]
	s_waitcnt vmcnt(24)
	v_lshlrev_b32_e32 v200, 16, v112
	v_and_b32_e32 v201, 0xffff0000, v112
	v_lshlrev_b32_e32 v112, 16, v113
	v_and_b32_e32 v113, 0xffff0000, v113
	v_pk_add_f32 v[28:29], v[28:29], v[200:201]
	v_pk_add_f32 v[30:31], v[30:31], v[112:113]
	v_mul_f32_e32 v198, v28, v28
	v_fmac_f32_e32 v198, v29, v29
	v_fmac_f32_e32 v198, v30, v30
	v_fmac_f32_e32 v198, v31, v31
	v_cvt_pk_bf16_f32 v28, v28, v29
	v_cvt_pk_bf16_f32 v29, v30, v31
	v_lshlrev_b32_e32 v200, 16, v114
	v_and_b32_e32 v201, 0xffff0000, v114
	v_lshlrev_b32_e32 v114, 16, v115
	v_and_b32_e32 v115, 0xffff0000, v115
	v_pk_add_f32 v[24:25], v[24:25], v[200:201]
	v_pk_add_f32 v[26:27], v[26:27], v[114:115]
	v_fmac_f32_e32 v198, v24, v24
	v_fmac_f32_e32 v198, v25, v25
	v_fmac_f32_e32 v198, v26, v26
	v_fmac_f32_e32 v198, v27, v27
	v_cvt_pk_bf16_f32 v24, v24, v25
	v_cvt_pk_bf16_f32 v25, v26, v27
	v_lshlrev_b32_e32 v200, 16, v116
	v_and_b32_e32 v201, 0xffff0000, v116
	v_lshlrev_b32_e32 v116, 16, v117
	v_and_b32_e32 v117, 0xffff0000, v117
	v_pk_add_f32 v[20:21], v[20:21], v[200:201]
	v_pk_add_f32 v[22:23], v[22:23], v[116:117]
	v_fmac_f32_e32 v198, v20, v20
	v_fmac_f32_e32 v198, v21, v21
	v_fmac_f32_e32 v198, v22, v22
	v_fmac_f32_e32 v198, v23, v23
	v_cvt_pk_bf16_f32 v20, v20, v21
	v_cvt_pk_bf16_f32 v21, v22, v23
	v_lshlrev_b32_e32 v200, 16, v118
	v_and_b32_e32 v201, 0xffff0000, v118
	v_lshlrev_b32_e32 v118, 16, v119
	v_and_b32_e32 v119, 0xffff0000, v119
	v_pk_add_f32 v[16:17], v[16:17], v[200:201]
	v_pk_add_f32 v[18:19], v[18:19], v[118:119]
	v_fmac_f32_e32 v198, v16, v16
	v_fmac_f32_e32 v198, v17, v17
	v_fmac_f32_e32 v198, v18, v18
	v_fmac_f32_e32 v198, v19, v19
	v_cvt_pk_bf16_f32 v16, v16, v17
	v_cvt_pk_bf16_f32 v17, v18, v19
	v_add_u32_e32 v197, 0x50000, v196
	global_store_dwordx2 v197, v[28:29], s[94:95]
	global_store_dwordx2 v197, v[24:25], s[94:95] offset:32
	global_store_dwordx2 v197, v[20:21], s[94:95] offset:256
	global_store_dwordx2 v197, v[16:17], s[94:95] offset:288
	ds_bpermute_b32 v199, v146, v198
	s_waitcnt lgkmcnt(0)
	v_add_f32_e32 v198, v198, v199
	ds_bpermute_b32 v199, v147, v198
	v_or_b32_e32 v197, 0xa0, v136
	v_lshlrev_b32_e32 v197, 2, v197
	s_waitcnt lgkmcnt(0)
	v_add_f32_e32 v198, v198, v199
	s_and_saveexec_b64 s[2:3], s[0:1]
	s_cbranch_execz .Lmy_er_skip6
	global_atomic_add_f32 v197, v198, s[14:15]
.Lmy_er_skip6:
	s_or_b64 exec, exec, s[2:3]
	s_waitcnt vmcnt(25)
	v_lshlrev_b32_e32 v200, 16, v120
	v_and_b32_e32 v201, 0xffff0000, v120
	v_lshlrev_b32_e32 v120, 16, v121
	v_and_b32_e32 v121, 0xffff0000, v121
	v_pk_add_f32 v[12:13], v[12:13], v[200:201]
	v_pk_add_f32 v[14:15], v[14:15], v[120:121]
	v_mul_f32_e32 v198, v12, v12
	v_fmac_f32_e32 v198, v13, v13
	v_fmac_f32_e32 v198, v14, v14
	v_fmac_f32_e32 v198, v15, v15
	v_cvt_pk_bf16_f32 v12, v12, v13
	v_cvt_pk_bf16_f32 v13, v14, v15
	v_lshlrev_b32_e32 v200, 16, v122
	v_and_b32_e32 v201, 0xffff0000, v122
	v_lshlrev_b32_e32 v122, 16, v123
	v_and_b32_e32 v123, 0xffff0000, v123
	v_pk_add_f32 v[8:9], v[8:9], v[200:201]
	v_pk_add_f32 v[10:11], v[10:11], v[122:123]
	v_fmac_f32_e32 v198, v8, v8
	v_fmac_f32_e32 v198, v9, v9
	v_fmac_f32_e32 v198, v10, v10
	v_fmac_f32_e32 v198, v11, v11
	v_cvt_pk_bf16_f32 v8, v8, v9
	v_cvt_pk_bf16_f32 v9, v10, v11
	v_lshlrev_b32_e32 v200, 16, v124
	v_and_b32_e32 v201, 0xffff0000, v124
	v_lshlrev_b32_e32 v124, 16, v125
	v_and_b32_e32 v125, 0xffff0000, v125
	v_pk_add_f32 v[4:5], v[4:5], v[200:201]
	v_pk_add_f32 v[6:7], v[6:7], v[124:125]
	v_fmac_f32_e32 v198, v4, v4
	v_fmac_f32_e32 v198, v5, v5
	v_fmac_f32_e32 v198, v6, v6
	v_fmac_f32_e32 v198, v7, v7
	v_cvt_pk_bf16_f32 v4, v4, v5
	v_cvt_pk_bf16_f32 v5, v6, v7
	v_lshlrev_b32_e32 v200, 16, v126
	v_and_b32_e32 v201, 0xffff0000, v126
	v_lshlrev_b32_e32 v126, 16, v127
	v_and_b32_e32 v127, 0xffff0000, v127
	v_pk_add_f32 v[0:1], v[0:1], v[200:201]
	v_pk_add_f32 v[2:3], v[2:3], v[126:127]
	v_fmac_f32_e32 v198, v0, v0
	v_fmac_f32_e32 v198, v1, v1
	v_fmac_f32_e32 v198, v2, v2
	v_fmac_f32_e32 v198, v3, v3
	v_cvt_pk_bf16_f32 v0, v0, v1
	v_cvt_pk_bf16_f32 v1, v2, v3
	v_add_u32_e32 v197, 0x58000, v196
	global_store_dwordx2 v197, v[12:13], s[94:95]
	global_store_dwordx2 v197, v[8:9], s[94:95] offset:32
	global_store_dwordx2 v197, v[4:5], s[94:95] offset:256
	global_store_dwordx2 v197, v[0:1], s[94:95] offset:288
	ds_bpermute_b32 v199, v146, v198
	s_waitcnt lgkmcnt(0)
	v_add_f32_e32 v198, v198, v199
	ds_bpermute_b32 v199, v147, v198
	v_or_b32_e32 v197, 0xb0, v136
	v_lshlrev_b32_e32 v197, 2, v197
	s_waitcnt lgkmcnt(0)
	v_add_f32_e32 v198, v198, v199
	s_and_saveexec_b64 s[2:3], s[0:1]
	s_cbranch_execz .Lmy_er_skip7
	global_atomic_add_f32 v197, v198, s[14:15]
